# v10 + GEMM loop-top: 16 fragment ds_reads issued before the next-tile address SALU block (6 loops), dropped redundant mid-segment lgkmcnt(0) in A1 loop
# baseline (speedup 1.0000x reference)
.LBB0_180:
	v_add_u32_e32 v148, 0x10000, v230
	v_add_u32_e32 v164, 0x14000, v230
	ds_read_b128 v[136:139], v148
	ds_read_b128 v[140:143], v148 offset:1024
	ds_read_b128 v[144:147], v148 offset:2048
	ds_read_b128 v[148:151], v148 offset:3072
	ds_read_b128 v[152:155], v164
	ds_read_b128 v[156:159], v164 offset:1024
	ds_read_b128 v[160:163], v164 offset:2048
	ds_read_b128 v[164:167], v164 offset:3072
	v_lshl_add_u64 v[196:197], v[132:133], 0, s[8:9]
	s_add_i32 m0, s39, 0xc000
	ds_read_b128 v[168:171], v242
	ds_read_b128 v[188:191], v242 offset:1024
	ds_read_b128 v[192:195], v242 offset:2048
	ds_read_b128 v[204:207], v242 offset:3072
	ds_read_b128 v[208:211], v242 offset:4096
	ds_read_b128 v[212:215], v242 offset:5120
	ds_read_b128 v[244:247], v242 offset:6144
	ds_read_b128 v[248:251], v242 offset:7168
	s_add_u32 s12, s26, s8
	s_addc_u32 s13, s27, s9
	s_add_u32 s12, s12, 0x100
	s_addc_u32 s13, s13, 0
	s_add_u32 s81, s67, s8
	s_addc_u32 s83, s43, s9
	s_add_i32 s95, 0, 0x10000
	s_cmpk_eq_i32 s8, 0xf00
	s_cselect_b32 s35, s25, s13
	s_cselect_b32 s34, s36, s12
	s_cselect_b32 s13, s23, s83
	s_cselect_b32 s12, s37, s81
	s_add_i32 s81, 0, 0x14000
	global_load_lds_dwordx4 v[196:197], off
	v_lshl_add_u64 v[196:197], v[134:135], 0, s[8:9]
	s_add_i32 m0, s39, 0xe000
	s_nop 0
	global_load_lds_dwordx4 v[196:197], off
	s_waitcnt vmcnt(8)
	s_waitcnt lgkmcnt(0)
	s_setprio 1
	s_barrier
	v_mfma_f32_16x16x32_bf16 v[8:11], v[136:139], v[168:171], v[8:11]
	v_mfma_f32_16x16x32_bf16 v[128:131], v[144:147], v[168:171], v[128:131]
	v_mfma_f32_16x16x32_bf16 v[124:127], v[136:139], v[192:195], v[124:127]
	v_mfma_f32_16x16x32_bf16 v[120:123], v[144:147], v[192:195], v[120:123]
	v_mfma_f32_16x16x32_bf16 v[116:119], v[136:139], v[208:211], v[116:119]
	v_mfma_f32_16x16x32_bf16 v[112:115], v[144:147], v[208:211], v[112:115]
	v_mfma_f32_16x16x32_bf16 v[108:111], v[136:139], v[244:247], v[108:111]
	v_mfma_f32_16x16x32_bf16 v[104:107], v[144:147], v[244:247], v[104:107]
	v_mfma_f32_16x16x32_bf16 v[8:11], v[140:143], v[188:191], v[8:11]
	v_mfma_f32_16x16x32_bf16 v[128:131], v[148:151], v[188:191], v[128:131]
	v_mfma_f32_16x16x32_bf16 v[124:127], v[140:143], v[204:207], v[124:127]
	v_mfma_f32_16x16x32_bf16 v[120:123], v[148:151], v[204:207], v[120:123]
	v_mfma_f32_16x16x32_bf16 v[116:119], v[140:143], v[212:215], v[116:119]
	v_mfma_f32_16x16x32_bf16 v[112:115], v[148:151], v[212:215], v[112:115]
	v_mfma_f32_16x16x32_bf16 v[108:111], v[140:143], v[248:251], v[108:111]
	v_mfma_f32_16x16x32_bf16 v[104:107], v[148:151], v[248:251], v[104:107]
	s_setprio 0
	s_setprio 1
	v_mfma_f32_16x16x32_bf16 v[100:103], v[152:155], v[168:171], v[100:103]
	v_mfma_f32_16x16x32_bf16 v[96:99], v[160:163], v[168:171], v[96:99]
	v_mfma_f32_16x16x32_bf16 v[92:95], v[152:155], v[192:195], v[92:95]
	v_mfma_f32_16x16x32_bf16 v[88:91], v[160:163], v[192:195], v[88:91]
	v_mfma_f32_16x16x32_bf16 v[84:87], v[152:155], v[208:211], v[84:87]
	v_mfma_f32_16x16x32_bf16 v[80:83], v[160:163], v[208:211], v[80:83]
	v_mfma_f32_16x16x32_bf16 v[76:79], v[152:155], v[244:247], v[76:79]
	v_mfma_f32_16x16x32_bf16 v[72:75], v[160:163], v[244:247], v[72:75]
	v_mfma_f32_16x16x32_bf16 v[100:103], v[156:159], v[188:191], v[100:103]
	v_mfma_f32_16x16x32_bf16 v[96:99], v[164:167], v[188:191], v[96:99]
	v_mfma_f32_16x16x32_bf16 v[92:95], v[156:159], v[204:207], v[92:95]
	v_mfma_f32_16x16x32_bf16 v[88:91], v[164:167], v[204:207], v[88:91]
	v_mfma_f32_16x16x32_bf16 v[84:87], v[156:159], v[212:215], v[84:87]
	v_mfma_f32_16x16x32_bf16 v[80:83], v[164:167], v[212:215], v[80:83]
	v_mfma_f32_16x16x32_bf16 v[76:79], v[156:159], v[248:251], v[76:79]
	v_mfma_f32_16x16x32_bf16 v[72:75], v[164:167], v[248:251], v[72:75]
	s_setprio 0
	s_barrier
	s_add_i32 s83, s95, s38
	v_lshl_add_u64 v[196:197], s[12:13], 0, v[172:173]
	s_mov_b32 m0, s83
	ds_read_b128 v[168:171], v242 offset:16384
	ds_read_b128 v[188:191], v242 offset:17408
	ds_read_b128 v[192:195], v242 offset:18432
	ds_read_b128 v[204:207], v242 offset:19456
	ds_read_b128 v[208:211], v242 offset:20480
	ds_read_b128 v[212:215], v242 offset:21504
	ds_read_b128 v[244:247], v242 offset:22528
	ds_read_b128 v[248:251], v242 offset:23552
	global_load_lds_dwordx4 v[196:197], off
	s_add_i32 m0, s83, 0x2000
	s_add_u32 vcc_lo, s12, 0x80000
	v_lshl_add_u64 v[198:199], s[12:13], 0, v[176:177]
	s_addc_u32 vcc_hi, s13, 0
	s_add_i32 s81, s81, s38
	global_load_lds_dwordx4 v[198:199], off
	v_lshl_add_u64 v[200:201], vcc, 0, v[172:173]
	s_mov_b32 m0, s81
	v_lshl_add_u64 v[202:203], s[34:35], 0, v[174:175]
	global_load_lds_dwordx4 v[200:201], off
	v_lshl_add_u64 v[200:201], vcc, 0, v[176:177]
	s_add_i32 m0, s81, 0x2000
	s_nop 0
	global_load_lds_dwordx4 v[200:201], off
	v_lshl_add_u64 v[200:201], s[34:35], 0, v[0:1]
	s_mov_b32 m0, s39
	s_nop 0
	global_load_lds_dwordx4 v[200:201], off
	s_mov_b32 m0, s46
	s_nop 0
	global_load_lds_dwordx4 v[202:203], off
	s_waitcnt vmcnt(8)
	s_waitcnt lgkmcnt(0)
	s_setprio 1
	s_barrier
	v_mfma_f32_16x16x32_bf16 v[68:71], v[136:139], v[168:171], v[68:71]
	v_mfma_f32_16x16x32_bf16 v[64:67], v[144:147], v[168:171], v[64:67]
	v_mfma_f32_16x16x32_bf16 v[60:63], v[136:139], v[192:195], v[60:63]
	v_mfma_f32_16x16x32_bf16 v[56:59], v[144:147], v[192:195], v[56:59]
	v_mfma_f32_16x16x32_bf16 v[52:55], v[136:139], v[208:211], v[52:55]
	v_mfma_f32_16x16x32_bf16 v[48:51], v[144:147], v[208:211], v[48:51]
	v_mfma_f32_16x16x32_bf16 v[44:47], v[136:139], v[244:247], v[44:47]
	v_mfma_f32_16x16x32_bf16 v[40:43], v[144:147], v[244:247], v[40:43]
	v_mfma_f32_16x16x32_bf16 v[68:71], v[140:143], v[188:191], v[68:71]
	v_mfma_f32_16x16x32_bf16 v[64:67], v[148:151], v[188:191], v[64:67]
	v_mfma_f32_16x16x32_bf16 v[60:63], v[140:143], v[204:207], v[60:63]
	v_mfma_f32_16x16x32_bf16 v[56:59], v[148:151], v[204:207], v[56:59]
	v_mfma_f32_16x16x32_bf16 v[52:55], v[140:143], v[212:215], v[52:55]
	v_mfma_f32_16x16x32_bf16 v[48:51], v[148:151], v[212:215], v[48:51]
	v_mfma_f32_16x16x32_bf16 v[44:47], v[140:143], v[248:251], v[44:47]
	v_mfma_f32_16x16x32_bf16 v[40:43], v[148:151], v[248:251], v[40:43]
	s_setprio 0
	s_setprio 1
	v_mfma_f32_16x16x32_bf16 v[36:39], v[152:155], v[168:171], v[36:39]
	v_mfma_f32_16x16x32_bf16 v[32:35], v[160:163], v[168:171], v[32:35]
	v_mfma_f32_16x16x32_bf16 v[28:31], v[152:155], v[192:195], v[28:31]
	v_mfma_f32_16x16x32_bf16 v[24:27], v[160:163], v[192:195], v[24:27]
	v_mfma_f32_16x16x32_bf16 v[20:23], v[152:155], v[208:211], v[20:23]
	v_mfma_f32_16x16x32_bf16 v[16:19], v[160:163], v[208:211], v[16:19]
	v_mfma_f32_16x16x32_bf16 v[12:15], v[152:155], v[244:247], v[12:15]
	v_mfma_f32_16x16x32_bf16 v[4:7], v[160:163], v[244:247], v[4:7]
	v_mfma_f32_16x16x32_bf16 v[36:39], v[156:159], v[188:191], v[36:39]
	v_mfma_f32_16x16x32_bf16 v[32:35], v[164:167], v[188:191], v[32:35]
	v_mfma_f32_16x16x32_bf16 v[28:31], v[156:159], v[204:207], v[28:31]
	v_mfma_f32_16x16x32_bf16 v[24:27], v[164:167], v[204:207], v[24:27]
	v_mfma_f32_16x16x32_bf16 v[20:23], v[156:159], v[212:215], v[20:23]
	v_mfma_f32_16x16x32_bf16 v[16:19], v[164:167], v[212:215], v[16:19]
	v_mfma_f32_16x16x32_bf16 v[12:15], v[156:159], v[248:251], v[12:15]
	v_mfma_f32_16x16x32_bf16 v[4:7], v[164:167], v[248:251], v[4:7]
	s_setprio 0
	s_barrier
	s_add_i32 s81, 0, 0x18000
	s_add_i32 s83, 0, 0x1c000
	v_add_u32_e32 v148, s81, v230
	v_add_u32_e32 v164, s83, v230
	ds_read_b128 v[136:139], v148
	ds_read_b128 v[140:143], v148 offset:1024
	ds_read_b128 v[144:147], v148 offset:2048
	ds_read_b128 v[148:151], v148 offset:3072
	ds_read_b128 v[152:155], v164
	ds_read_b128 v[156:159], v164 offset:1024
	ds_read_b128 v[160:163], v164 offset:2048
	ds_read_b128 v[164:167], v164 offset:3072
	s_add_u32 s34, s34, 0x80000
	s_addc_u32 s35, s35, 0
	s_mov_b32 m0, s47
	v_lshl_add_u64 v[216:217], s[34:35], 0, v[0:1]
	ds_read_b128 v[168:171], v242 offset:32768
	ds_read_b128 v[188:191], v242 offset:33792
	ds_read_b128 v[192:195], v242 offset:34816
	ds_read_b128 v[204:207], v242 offset:35840
	ds_read_b128 v[208:211], v242 offset:36864
	ds_read_b128 v[212:215], v242 offset:37888
	ds_read_b128 v[244:247], v242 offset:38912
	ds_read_b128 v[248:251], v242 offset:39936
	global_load_lds_dwordx4 v[216:217], off
	v_lshl_add_u64 v[216:217], s[34:35], 0, v[174:175]
	s_mov_b32 m0, s51
	s_nop 0
	global_load_lds_dwordx4 v[216:217], off
	s_waitcnt vmcnt(8)
	s_waitcnt lgkmcnt(0)
	s_setprio 1
	s_barrier
	v_mfma_f32_16x16x32_bf16 v[8:11], v[136:139], v[168:171], v[8:11]
	v_mfma_f32_16x16x32_bf16 v[128:131], v[144:147], v[168:171], v[128:131]
	v_mfma_f32_16x16x32_bf16 v[124:127], v[136:139], v[192:195], v[124:127]
	v_mfma_f32_16x16x32_bf16 v[120:123], v[144:147], v[192:195], v[120:123]
	v_mfma_f32_16x16x32_bf16 v[116:119], v[136:139], v[208:211], v[116:119]
	v_mfma_f32_16x16x32_bf16 v[112:115], v[144:147], v[208:211], v[112:115]
	v_mfma_f32_16x16x32_bf16 v[108:111], v[136:139], v[244:247], v[108:111]
	v_mfma_f32_16x16x32_bf16 v[104:107], v[144:147], v[244:247], v[104:107]
	v_mfma_f32_16x16x32_bf16 v[8:11], v[140:143], v[188:191], v[8:11]
	v_mfma_f32_16x16x32_bf16 v[128:131], v[148:151], v[188:191], v[128:131]
	v_mfma_f32_16x16x32_bf16 v[124:127], v[140:143], v[204:207], v[124:127]
	v_mfma_f32_16x16x32_bf16 v[120:123], v[148:151], v[204:207], v[120:123]
	v_mfma_f32_16x16x32_bf16 v[116:119], v[140:143], v[212:215], v[116:119]
	v_mfma_f32_16x16x32_bf16 v[112:115], v[148:151], v[212:215], v[112:115]
	v_mfma_f32_16x16x32_bf16 v[108:111], v[140:143], v[248:251], v[108:111]
	v_mfma_f32_16x16x32_bf16 v[104:107], v[148:151], v[248:251], v[104:107]
	s_setprio 0
	s_setprio 1
	v_mfma_f32_16x16x32_bf16 v[100:103], v[152:155], v[168:171], v[100:103]
	v_mfma_f32_16x16x32_bf16 v[96:99], v[160:163], v[168:171], v[96:99]
	v_mfma_f32_16x16x32_bf16 v[92:95], v[152:155], v[192:195], v[92:95]
	v_mfma_f32_16x16x32_bf16 v[88:91], v[160:163], v[192:195], v[88:91]
	v_mfma_f32_16x16x32_bf16 v[84:87], v[152:155], v[208:211], v[84:87]
	v_mfma_f32_16x16x32_bf16 v[80:83], v[160:163], v[208:211], v[80:83]
	v_mfma_f32_16x16x32_bf16 v[76:79], v[152:155], v[244:247], v[76:79]
	v_mfma_f32_16x16x32_bf16 v[72:75], v[160:163], v[244:247], v[72:75]
	v_mfma_f32_16x16x32_bf16 v[100:103], v[156:159], v[188:191], v[100:103]
	v_mfma_f32_16x16x32_bf16 v[96:99], v[164:167], v[188:191], v[96:99]
	v_mfma_f32_16x16x32_bf16 v[92:95], v[156:159], v[204:207], v[92:95]
	v_mfma_f32_16x16x32_bf16 v[88:91], v[164:167], v[204:207], v[88:91]
	v_mfma_f32_16x16x32_bf16 v[84:87], v[156:159], v[212:215], v[84:87]
	v_mfma_f32_16x16x32_bf16 v[80:83], v[164:167], v[212:215], v[80:83]
	v_mfma_f32_16x16x32_bf16 v[76:79], v[156:159], v[248:251], v[76:79]
	v_mfma_f32_16x16x32_bf16 v[72:75], v[164:167], v[248:251], v[72:75]
	s_setprio 0
	s_barrier
	s_add_i32 s34, s81, s38
	v_lshl_add_u64 v[196:197], v[196:197], 0, s[70:71]
	s_mov_b32 m0, s34
	ds_read_b128 v[168:171], v242 offset:49152
	ds_read_b128 v[188:191], v242 offset:50176
	ds_read_b128 v[192:195], v242 offset:51200
	ds_read_b128 v[204:207], v242 offset:52224
	ds_read_b128 v[208:211], v242 offset:53248
	ds_read_b128 v[212:215], v242 offset:54272
	ds_read_b128 v[244:247], v242 offset:55296
	ds_read_b128 v[248:251], v242 offset:56320
	global_load_lds_dwordx4 v[196:197], off
	s_add_i32 m0, s34, 0x2000
	s_add_u32 s12, s12, 0x80080
	v_lshl_add_u64 v[196:197], v[198:199], 0, s[70:71]
	s_addc_u32 s13, s13, 0
	s_add_i32 s34, s83, s38
	global_load_lds_dwordx4 v[196:197], off
	v_lshl_add_u64 v[196:197], s[12:13], 0, v[172:173]
	s_mov_b32 m0, s34
	s_nop 0
	global_load_lds_dwordx4 v[196:197], off
	v_lshl_add_u64 v[196:197], s[12:13], 0, v[176:177]
	s_add_i32 m0, s34, 0x2000
	s_nop 0
	global_load_lds_dwordx4 v[196:197], off
	v_lshl_add_u64 v[196:197], v[200:201], 0, s[70:71]
	s_mov_b32 m0, s74
	s_nop 0
	global_load_lds_dwordx4 v[196:197], off
	v_lshl_add_u64 v[196:197], v[202:203], 0, s[70:71]
	s_mov_b32 m0, s75
	s_nop 0
	global_load_lds_dwordx4 v[196:197], off
	s_waitcnt vmcnt(8)
	s_waitcnt lgkmcnt(0)
	s_setprio 1
	s_barrier
	v_mfma_f32_16x16x32_bf16 v[68:71], v[136:139], v[168:171], v[68:71]
	v_mfma_f32_16x16x32_bf16 v[64:67], v[144:147], v[168:171], v[64:67]
	v_mfma_f32_16x16x32_bf16 v[60:63], v[136:139], v[192:195], v[60:63]
	v_mfma_f32_16x16x32_bf16 v[56:59], v[144:147], v[192:195], v[56:59]
	v_mfma_f32_16x16x32_bf16 v[52:55], v[136:139], v[208:211], v[52:55]
	v_mfma_f32_16x16x32_bf16 v[48:51], v[144:147], v[208:211], v[48:51]
	v_mfma_f32_16x16x32_bf16 v[44:47], v[136:139], v[244:247], v[44:47]
	v_mfma_f32_16x16x32_bf16 v[40:43], v[144:147], v[244:247], v[40:43]
	v_mfma_f32_16x16x32_bf16 v[68:71], v[140:143], v[188:191], v[68:71]
	v_mfma_f32_16x16x32_bf16 v[64:67], v[148:151], v[188:191], v[64:67]
	v_mfma_f32_16x16x32_bf16 v[60:63], v[140:143], v[204:207], v[60:63]
	v_mfma_f32_16x16x32_bf16 v[56:59], v[148:151], v[204:207], v[56:59]
	v_mfma_f32_16x16x32_bf16 v[52:55], v[140:143], v[212:215], v[52:55]
	v_mfma_f32_16x16x32_bf16 v[48:51], v[148:151], v[212:215], v[48:51]
	v_mfma_f32_16x16x32_bf16 v[44:47], v[140:143], v[248:251], v[44:47]
	v_mfma_f32_16x16x32_bf16 v[40:43], v[148:151], v[248:251], v[40:43]
	s_setprio 0
	s_setprio 1
	v_mfma_f32_16x16x32_bf16 v[36:39], v[152:155], v[168:171], v[36:39]
	v_mfma_f32_16x16x32_bf16 v[32:35], v[160:163], v[168:171], v[32:35]
	v_mfma_f32_16x16x32_bf16 v[28:31], v[152:155], v[192:195], v[28:31]
	v_mfma_f32_16x16x32_bf16 v[24:27], v[160:163], v[192:195], v[24:27]
	v_mfma_f32_16x16x32_bf16 v[20:23], v[152:155], v[208:211], v[20:23]
	v_mfma_f32_16x16x32_bf16 v[16:19], v[160:163], v[208:211], v[16:19]
	v_mfma_f32_16x16x32_bf16 v[12:15], v[152:155], v[244:247], v[12:15]
	v_mfma_f32_16x16x32_bf16 v[4:7], v[160:163], v[244:247], v[4:7]
	v_mfma_f32_16x16x32_bf16 v[36:39], v[156:159], v[188:191], v[36:39]
	v_mfma_f32_16x16x32_bf16 v[32:35], v[164:167], v[188:191], v[32:35]
	v_mfma_f32_16x16x32_bf16 v[28:31], v[156:159], v[204:207], v[28:31]
	v_mfma_f32_16x16x32_bf16 v[24:27], v[164:167], v[204:207], v[24:27]
	v_mfma_f32_16x16x32_bf16 v[20:23], v[156:159], v[212:215], v[20:23]
	v_mfma_f32_16x16x32_bf16 v[16:19], v[164:167], v[212:215], v[16:19]
	v_mfma_f32_16x16x32_bf16 v[12:15], v[156:159], v[248:251], v[12:15]
	v_mfma_f32_16x16x32_bf16 v[4:7], v[164:167], v[248:251], v[4:7]
	s_setprio 0
	s_barrier
	s_add_i32 s42, s42, 2
	s_add_u32 s8, s8, 0x100
	s_addc_u32 s9, s9, 0
	s_cmp_gt_u32 s42, 29
	s_cbranch_scc0 .LBB0_180
	s_and_b64 vcc, exec, s[20:21]
	s_cbranch_vccz .LBB0_183
	s_barrier

.LBB0_319:
	v_add_u32_e32 v148, 0x10000, v229
	v_add_u32_e32 v164, 0x14000, v229
	ds_read_b128 v[136:139], v148
	ds_read_b128 v[140:143], v148 offset:1024
	ds_read_b128 v[144:147], v148 offset:2048
	ds_read_b128 v[148:151], v148 offset:3072
	ds_read_b128 v[152:155], v164
	ds_read_b128 v[156:159], v164 offset:1024
	ds_read_b128 v[160:163], v164 offset:2048
	ds_read_b128 v[164:167], v164 offset:3072
	v_lshl_add_u64 v[194:195], v[132:133], 0, s[8:9]
	s_add_i32 m0, s39, 0xc000
	ds_read_b128 v[168:171], v242
	ds_read_b128 v[186:189], v242 offset:1024
	ds_read_b128 v[190:193], v242 offset:2048
	ds_read_b128 v[204:207], v242 offset:3072
	ds_read_b128 v[208:211], v242 offset:4096
	ds_read_b128 v[212:215], v242 offset:5120
	ds_read_b128 v[244:247], v242 offset:6144
	ds_read_b128 v[248:251], v242 offset:7168
	s_add_u32 s12, s28, s8
	s_addc_u32 s13, s29, s9
	s_add_u32 s12, s12, 0x100
	s_addc_u32 s13, s13, 0
	s_add_u32 s43, s92, s8
	s_addc_u32 s66, s93, s9
	s_add_i32 s67, 0, 0x10000
	s_cmpk_eq_i32 s8, 0xf00
	s_cselect_b32 s17, s27, s13
	s_cselect_b32 s16, s36, s12
	s_cselect_b32 s13, s25, s66
	s_cselect_b32 s12, s37, s43
	s_add_i32 s43, 0, 0x14000
	global_load_lds_dwordx4 v[194:195], off
	v_lshl_add_u64 v[194:195], v[134:135], 0, s[8:9]
	s_add_i32 m0, s39, 0xe000
	s_nop 0
	global_load_lds_dwordx4 v[194:195], off
	s_waitcnt vmcnt(8)
	s_waitcnt lgkmcnt(0)
	s_setprio 1
	s_barrier
	v_mfma_f32_16x16x32_bf16 v[8:11], v[136:139], v[168:171], v[8:11]
	v_mfma_f32_16x16x32_bf16 v[128:131], v[144:147], v[168:171], v[128:131]
	v_mfma_f32_16x16x32_bf16 v[124:127], v[136:139], v[190:193], v[124:127]
	v_mfma_f32_16x16x32_bf16 v[120:123], v[144:147], v[190:193], v[120:123]
	v_mfma_f32_16x16x32_bf16 v[116:119], v[136:139], v[208:211], v[116:119]
	v_mfma_f32_16x16x32_bf16 v[112:115], v[144:147], v[208:211], v[112:115]
	v_mfma_f32_16x16x32_bf16 v[108:111], v[136:139], v[244:247], v[108:111]
	v_mfma_f32_16x16x32_bf16 v[104:107], v[144:147], v[244:247], v[104:107]
	v_mfma_f32_16x16x32_bf16 v[8:11], v[140:143], v[186:189], v[8:11]
	v_mfma_f32_16x16x32_bf16 v[128:131], v[148:151], v[186:189], v[128:131]
	v_mfma_f32_16x16x32_bf16 v[124:127], v[140:143], v[204:207], v[124:127]
	v_mfma_f32_16x16x32_bf16 v[120:123], v[148:151], v[204:207], v[120:123]
	v_mfma_f32_16x16x32_bf16 v[116:119], v[140:143], v[212:215], v[116:119]
	v_mfma_f32_16x16x32_bf16 v[112:115], v[148:151], v[212:215], v[112:115]
	v_mfma_f32_16x16x32_bf16 v[108:111], v[140:143], v[248:251], v[108:111]
	v_mfma_f32_16x16x32_bf16 v[104:107], v[148:151], v[248:251], v[104:107]
	s_setprio 0
	s_setprio 1
	v_mfma_f32_16x16x32_bf16 v[100:103], v[152:155], v[168:171], v[100:103]
	v_mfma_f32_16x16x32_bf16 v[96:99], v[160:163], v[168:171], v[96:99]
	v_mfma_f32_16x16x32_bf16 v[92:95], v[152:155], v[190:193], v[92:95]
	v_mfma_f32_16x16x32_bf16 v[88:91], v[160:163], v[190:193], v[88:91]
	v_mfma_f32_16x16x32_bf16 v[84:87], v[152:155], v[208:211], v[84:87]
	v_mfma_f32_16x16x32_bf16 v[80:83], v[160:163], v[208:211], v[80:83]
	v_mfma_f32_16x16x32_bf16 v[76:79], v[152:155], v[244:247], v[76:79]
	v_mfma_f32_16x16x32_bf16 v[72:75], v[160:163], v[244:247], v[72:75]
	v_mfma_f32_16x16x32_bf16 v[100:103], v[156:159], v[186:189], v[100:103]
	v_mfma_f32_16x16x32_bf16 v[96:99], v[164:167], v[186:189], v[96:99]
	v_mfma_f32_16x16x32_bf16 v[92:95], v[156:159], v[204:207], v[92:95]
	v_mfma_f32_16x16x32_bf16 v[88:91], v[164:167], v[204:207], v[88:91]
	v_mfma_f32_16x16x32_bf16 v[84:87], v[156:159], v[212:215], v[84:87]
	v_mfma_f32_16x16x32_bf16 v[80:83], v[164:167], v[212:215], v[80:83]
	v_mfma_f32_16x16x32_bf16 v[76:79], v[156:159], v[248:251], v[76:79]
	v_mfma_f32_16x16x32_bf16 v[72:75], v[164:167], v[248:251], v[72:75]
	s_setprio 0
	s_barrier
	s_add_i32 s66, s67, s38
	v_lshl_add_u64 v[194:195], s[12:13], 0, v[172:173]
	s_mov_b32 m0, s66
	ds_read_b128 v[168:171], v242 offset:16384
	ds_read_b128 v[186:189], v242 offset:17408
	ds_read_b128 v[190:193], v242 offset:18432
	ds_read_b128 v[204:207], v242 offset:19456
	ds_read_b128 v[208:211], v242 offset:20480
	ds_read_b128 v[212:215], v242 offset:21504
	ds_read_b128 v[244:247], v242 offset:22528
	ds_read_b128 v[248:251], v242 offset:23552
	global_load_lds_dwordx4 v[194:195], off
	s_add_i32 m0, s66, 0x2000
	s_add_u32 s66, s12, 0x80000
	v_lshl_add_u64 v[196:197], s[12:13], 0, v[176:177]
	s_addc_u32 s67, s13, 0
	s_add_i32 s43, s43, s38
	global_load_lds_dwordx4 v[196:197], off
	v_lshl_add_u64 v[198:199], s[66:67], 0, v[172:173]
	s_mov_b32 m0, s43
	v_lshl_add_u64 v[200:201], s[16:17], 0, v[174:175]
	global_load_lds_dwordx4 v[198:199], off
	v_lshl_add_u64 v[198:199], s[66:67], 0, v[176:177]
	s_add_i32 m0, s43, 0x2000
	s_nop 0
	global_load_lds_dwordx4 v[198:199], off
	v_lshl_add_u64 v[198:199], s[16:17], 0, v[0:1]
	s_mov_b32 m0, s39
	s_nop 0
	global_load_lds_dwordx4 v[198:199], off
	s_mov_b32 m0, s46
	s_nop 0
	global_load_lds_dwordx4 v[200:201], off
	s_waitcnt vmcnt(8)
	s_waitcnt lgkmcnt(0)
	s_setprio 1
	s_barrier
	v_mfma_f32_16x16x32_bf16 v[68:71], v[136:139], v[168:171], v[68:71]
	v_mfma_f32_16x16x32_bf16 v[64:67], v[144:147], v[168:171], v[64:67]
	v_mfma_f32_16x16x32_bf16 v[60:63], v[136:139], v[190:193], v[60:63]
	v_mfma_f32_16x16x32_bf16 v[56:59], v[144:147], v[190:193], v[56:59]
	v_mfma_f32_16x16x32_bf16 v[52:55], v[136:139], v[208:211], v[52:55]
	v_mfma_f32_16x16x32_bf16 v[48:51], v[144:147], v[208:211], v[48:51]
	v_mfma_f32_16x16x32_bf16 v[44:47], v[136:139], v[244:247], v[44:47]
	v_mfma_f32_16x16x32_bf16 v[40:43], v[144:147], v[244:247], v[40:43]
	v_mfma_f32_16x16x32_bf16 v[68:71], v[140:143], v[186:189], v[68:71]
	v_mfma_f32_16x16x32_bf16 v[64:67], v[148:151], v[186:189], v[64:67]
	v_mfma_f32_16x16x32_bf16 v[60:63], v[140:143], v[204:207], v[60:63]
	v_mfma_f32_16x16x32_bf16 v[56:59], v[148:151], v[204:207], v[56:59]
	v_mfma_f32_16x16x32_bf16 v[52:55], v[140:143], v[212:215], v[52:55]
	v_mfma_f32_16x16x32_bf16 v[48:51], v[148:151], v[212:215], v[48:51]
	v_mfma_f32_16x16x32_bf16 v[44:47], v[140:143], v[248:251], v[44:47]
	v_mfma_f32_16x16x32_bf16 v[40:43], v[148:151], v[248:251], v[40:43]
	s_setprio 0
	s_setprio 1
	v_mfma_f32_16x16x32_bf16 v[36:39], v[152:155], v[168:171], v[36:39]
	v_mfma_f32_16x16x32_bf16 v[32:35], v[160:163], v[168:171], v[32:35]
	v_mfma_f32_16x16x32_bf16 v[28:31], v[152:155], v[190:193], v[28:31]
	v_mfma_f32_16x16x32_bf16 v[24:27], v[160:163], v[190:193], v[24:27]
	v_mfma_f32_16x16x32_bf16 v[20:23], v[152:155], v[208:211], v[20:23]
	v_mfma_f32_16x16x32_bf16 v[16:19], v[160:163], v[208:211], v[16:19]
	v_mfma_f32_16x16x32_bf16 v[12:15], v[152:155], v[244:247], v[12:15]
	v_mfma_f32_16x16x32_bf16 v[4:7], v[160:163], v[244:247], v[4:7]
	v_mfma_f32_16x16x32_bf16 v[36:39], v[156:159], v[186:189], v[36:39]
	v_mfma_f32_16x16x32_bf16 v[32:35], v[164:167], v[186:189], v[32:35]
	v_mfma_f32_16x16x32_bf16 v[28:31], v[156:159], v[204:207], v[28:31]
	v_mfma_f32_16x16x32_bf16 v[24:27], v[164:167], v[204:207], v[24:27]
	v_mfma_f32_16x16x32_bf16 v[20:23], v[156:159], v[212:215], v[20:23]
	v_mfma_f32_16x16x32_bf16 v[16:19], v[164:167], v[212:215], v[16:19]
	v_mfma_f32_16x16x32_bf16 v[12:15], v[156:159], v[248:251], v[12:15]
	v_mfma_f32_16x16x32_bf16 v[4:7], v[164:167], v[248:251], v[4:7]
	s_setprio 0
	s_barrier
	s_add_i32 s43, 0, 0x18000
	s_add_i32 s66, 0, 0x1c000
	v_add_u32_e32 v148, s43, v229
	v_add_u32_e32 v164, s66, v229
	ds_read_b128 v[136:139], v148
	ds_read_b128 v[140:143], v148 offset:1024
	ds_read_b128 v[144:147], v148 offset:2048
	ds_read_b128 v[148:151], v148 offset:3072
	ds_read_b128 v[152:155], v164
	ds_read_b128 v[156:159], v164 offset:1024
	ds_read_b128 v[160:163], v164 offset:2048
	ds_read_b128 v[164:167], v164 offset:3072
	s_add_u32 s16, s16, 0x80000
	s_addc_u32 s17, s17, 0
	s_mov_b32 m0, s47
	v_lshl_add_u64 v[202:203], s[16:17], 0, v[0:1]
	ds_read_b128 v[168:171], v242 offset:32768
	ds_read_b128 v[186:189], v242 offset:33792
	ds_read_b128 v[190:193], v242 offset:34816
	ds_read_b128 v[204:207], v242 offset:35840
	ds_read_b128 v[208:211], v242 offset:36864
	ds_read_b128 v[212:215], v242 offset:37888
	ds_read_b128 v[244:247], v242 offset:38912
	ds_read_b128 v[248:251], v242 offset:39936
	global_load_lds_dwordx4 v[202:203], off
	v_lshl_add_u64 v[202:203], s[16:17], 0, v[174:175]
	s_mov_b32 m0, s51
	s_nop 0
	global_load_lds_dwordx4 v[202:203], off
	s_waitcnt vmcnt(8)
	s_waitcnt lgkmcnt(0)
	s_setprio 1
	s_barrier
	v_mfma_f32_16x16x32_bf16 v[8:11], v[136:139], v[168:171], v[8:11]
	v_mfma_f32_16x16x32_bf16 v[128:131], v[144:147], v[168:171], v[128:131]
	v_mfma_f32_16x16x32_bf16 v[124:127], v[136:139], v[190:193], v[124:127]
	v_mfma_f32_16x16x32_bf16 v[120:123], v[144:147], v[190:193], v[120:123]
	v_mfma_f32_16x16x32_bf16 v[116:119], v[136:139], v[208:211], v[116:119]
	v_mfma_f32_16x16x32_bf16 v[112:115], v[144:147], v[208:211], v[112:115]
	v_mfma_f32_16x16x32_bf16 v[108:111], v[136:139], v[244:247], v[108:111]
	v_mfma_f32_16x16x32_bf16 v[104:107], v[144:147], v[244:247], v[104:107]
	v_mfma_f32_16x16x32_bf16 v[8:11], v[140:143], v[186:189], v[8:11]
	v_mfma_f32_16x16x32_bf16 v[128:131], v[148:151], v[186:189], v[128:131]
	v_mfma_f32_16x16x32_bf16 v[124:127], v[140:143], v[204:207], v[124:127]
	v_mfma_f32_16x16x32_bf16 v[120:123], v[148:151], v[204:207], v[120:123]
	v_mfma_f32_16x16x32_bf16 v[116:119], v[140:143], v[212:215], v[116:119]
	v_mfma_f32_16x16x32_bf16 v[112:115], v[148:151], v[212:215], v[112:115]
	v_mfma_f32_16x16x32_bf16 v[108:111], v[140:143], v[248:251], v[108:111]
	v_mfma_f32_16x16x32_bf16 v[104:107], v[148:151], v[248:251], v[104:107]
	s_setprio 0
	s_setprio 1
	v_mfma_f32_16x16x32_bf16 v[100:103], v[152:155], v[168:171], v[100:103]
	v_mfma_f32_16x16x32_bf16 v[96:99], v[160:163], v[168:171], v[96:99]
	v_mfma_f32_16x16x32_bf16 v[92:95], v[152:155], v[190:193], v[92:95]
	v_mfma_f32_16x16x32_bf16 v[88:91], v[160:163], v[190:193], v[88:91]
	v_mfma_f32_16x16x32_bf16 v[84:87], v[152:155], v[208:211], v[84:87]
	v_mfma_f32_16x16x32_bf16 v[80:83], v[160:163], v[208:211], v[80:83]
	v_mfma_f32_16x16x32_bf16 v[76:79], v[152:155], v[244:247], v[76:79]
	v_mfma_f32_16x16x32_bf16 v[72:75], v[160:163], v[244:247], v[72:75]
	v_mfma_f32_16x16x32_bf16 v[100:103], v[156:159], v[186:189], v[100:103]
	v_mfma_f32_16x16x32_bf16 v[96:99], v[164:167], v[186:189], v[96:99]
	v_mfma_f32_16x16x32_bf16 v[92:95], v[156:159], v[204:207], v[92:95]
	v_mfma_f32_16x16x32_bf16 v[88:91], v[164:167], v[204:207], v[88:91]
	v_mfma_f32_16x16x32_bf16 v[84:87], v[156:159], v[212:215], v[84:87]
	v_mfma_f32_16x16x32_bf16 v[80:83], v[164:167], v[212:215], v[80:83]
	v_mfma_f32_16x16x32_bf16 v[76:79], v[156:159], v[248:251], v[76:79]
	v_mfma_f32_16x16x32_bf16 v[72:75], v[164:167], v[248:251], v[72:75]
	s_setprio 0
	s_barrier
	s_add_i32 s16, s43, s38
	v_lshl_add_u64 v[194:195], v[194:195], 0, s[70:71]
	s_mov_b32 m0, s16
	ds_read_b128 v[168:171], v242 offset:49152
	ds_read_b128 v[186:189], v242 offset:50176
	ds_read_b128 v[190:193], v242 offset:51200
	ds_read_b128 v[204:207], v242 offset:52224
	ds_read_b128 v[208:211], v242 offset:53248
	ds_read_b128 v[212:215], v242 offset:54272
	ds_read_b128 v[244:247], v242 offset:55296
	ds_read_b128 v[248:251], v242 offset:56320
	global_load_lds_dwordx4 v[194:195], off
	s_add_i32 m0, s16, 0x2000
	s_add_u32 s12, s12, 0x80080
	v_lshl_add_u64 v[194:195], v[196:197], 0, s[70:71]
	s_addc_u32 s13, s13, 0
	s_add_i32 s16, s66, s38
	global_load_lds_dwordx4 v[194:195], off
	v_lshl_add_u64 v[194:195], s[12:13], 0, v[172:173]
	s_mov_b32 m0, s16
	s_nop 0
	global_load_lds_dwordx4 v[194:195], off
	v_lshl_add_u64 v[194:195], s[12:13], 0, v[176:177]
	s_add_i32 m0, s16, 0x2000
	s_nop 0
	global_load_lds_dwordx4 v[194:195], off
	v_lshl_add_u64 v[194:195], v[198:199], 0, s[70:71]
	s_mov_b32 m0, s52
	s_nop 0
	global_load_lds_dwordx4 v[194:195], off
	v_lshl_add_u64 v[194:195], v[200:201], 0, s[70:71]
	s_mov_b32 m0, s54
	s_nop 0
	global_load_lds_dwordx4 v[194:195], off
	s_waitcnt vmcnt(8)
	s_waitcnt lgkmcnt(0)
	s_setprio 1
	s_barrier
	v_mfma_f32_16x16x32_bf16 v[68:71], v[136:139], v[168:171], v[68:71]
	v_mfma_f32_16x16x32_bf16 v[64:67], v[144:147], v[168:171], v[64:67]
	v_mfma_f32_16x16x32_bf16 v[60:63], v[136:139], v[190:193], v[60:63]
	v_mfma_f32_16x16x32_bf16 v[56:59], v[144:147], v[190:193], v[56:59]
	v_mfma_f32_16x16x32_bf16 v[52:55], v[136:139], v[208:211], v[52:55]
	v_mfma_f32_16x16x32_bf16 v[48:51], v[144:147], v[208:211], v[48:51]
	v_mfma_f32_16x16x32_bf16 v[44:47], v[136:139], v[244:247], v[44:47]
	v_mfma_f32_16x16x32_bf16 v[40:43], v[144:147], v[244:247], v[40:43]
	v_mfma_f32_16x16x32_bf16 v[68:71], v[140:143], v[186:189], v[68:71]
	v_mfma_f32_16x16x32_bf16 v[64:67], v[148:151], v[186:189], v[64:67]
	v_mfma_f32_16x16x32_bf16 v[60:63], v[140:143], v[204:207], v[60:63]
	v_mfma_f32_16x16x32_bf16 v[56:59], v[148:151], v[204:207], v[56:59]
	v_mfma_f32_16x16x32_bf16 v[52:55], v[140:143], v[212:215], v[52:55]
	v_mfma_f32_16x16x32_bf16 v[48:51], v[148:151], v[212:215], v[48:51]
	v_mfma_f32_16x16x32_bf16 v[44:47], v[140:143], v[248:251], v[44:47]
	v_mfma_f32_16x16x32_bf16 v[40:43], v[148:151], v[248:251], v[40:43]
	s_setprio 0
	s_setprio 1
	v_mfma_f32_16x16x32_bf16 v[36:39], v[152:155], v[168:171], v[36:39]
	v_mfma_f32_16x16x32_bf16 v[32:35], v[160:163], v[168:171], v[32:35]
	v_mfma_f32_16x16x32_bf16 v[28:31], v[152:155], v[190:193], v[28:31]
	v_mfma_f32_16x16x32_bf16 v[24:27], v[160:163], v[190:193], v[24:27]
	v_mfma_f32_16x16x32_bf16 v[20:23], v[152:155], v[208:211], v[20:23]
	v_mfma_f32_16x16x32_bf16 v[16:19], v[160:163], v[208:211], v[16:19]
	v_mfma_f32_16x16x32_bf16 v[12:15], v[152:155], v[244:247], v[12:15]
	v_mfma_f32_16x16x32_bf16 v[4:7], v[160:163], v[244:247], v[4:7]
	v_mfma_f32_16x16x32_bf16 v[36:39], v[156:159], v[186:189], v[36:39]
	v_mfma_f32_16x16x32_bf16 v[32:35], v[164:167], v[186:189], v[32:35]
	v_mfma_f32_16x16x32_bf16 v[28:31], v[156:159], v[204:207], v[28:31]
	v_mfma_f32_16x16x32_bf16 v[24:27], v[164:167], v[204:207], v[24:27]
	v_mfma_f32_16x16x32_bf16 v[20:23], v[156:159], v[212:215], v[20:23]
	v_mfma_f32_16x16x32_bf16 v[16:19], v[164:167], v[212:215], v[16:19]
	v_mfma_f32_16x16x32_bf16 v[12:15], v[156:159], v[248:251], v[12:15]
	v_mfma_f32_16x16x32_bf16 v[4:7], v[164:167], v[248:251], v[4:7]
	s_setprio 0
	s_barrier
	s_add_i32 s42, s42, 2
	s_add_u32 s8, s8, 0x100
	s_addc_u32 s9, s9, 0
	s_cmp_gt_u32 s42, 29
	s_cbranch_scc0 .LBB0_319
	s_and_b64 vcc, exec, s[22:23]
	s_cbranch_vccz .LBB0_322
	s_barrier

.LBB0_803:
	v_add_u32_e32 v148, 0x10000, v207
	v_add_u32_e32 v176, 0x14000, v207
	ds_read_b128 v[136:139], v148
	ds_read_b128 v[140:143], v148 offset:1024
	ds_read_b128 v[144:147], v148 offset:2048
	ds_read_b128 v[148:151], v148 offset:3072
	ds_read_b128 v[152:155], v176
	ds_read_b128 v[156:159], v176 offset:1024
	ds_read_b128 v[160:163], v176 offset:2048
	ds_read_b128 v[176:179], v176 offset:3072
	v_lshl_add_u64 v[196:197], v[132:133], 0, s[8:9]
	s_add_i32 m0, s75, 0xc000
	ds_read_b128 v[180:183], v209
	ds_read_b128 v[184:187], v209 offset:1024
	ds_read_b128 v[188:191], v209 offset:2048
	ds_read_b128 v[192:195], v209 offset:3072
	ds_read_b128 v[212:215], v209 offset:4096
	ds_read_b128 v[226:229], v209 offset:5120
	ds_read_b128 v[230:233], v209 offset:6144
	ds_read_b128 v[234:237], v209 offset:7168
	s_add_u32 s12, s28, s8
	s_addc_u32 s13, s29, s9
	s_add_u32 s12, s12, 0x100
	s_addc_u32 s13, s13, 0
	s_add_u32 s81, s84, s8
	s_addc_u32 s83, s85, s9
	s_add_i32 s95, 0, 0x10000
	s_cmpk_eq_i32 s8, 0xf00
	s_cselect_b32 s37, s27, s13
	s_cselect_b32 s36, s42, s12
	s_cselect_b32 s13, s25, s83
	s_cselect_b32 s12, s43, s81
	s_add_i32 s81, 0, 0x14000
	global_load_lds_dwordx4 v[196:197], off
	v_lshl_add_u64 v[196:197], v[134:135], 0, s[8:9]
	s_add_i32 m0, s75, 0xe000
	s_nop 0
	global_load_lds_dwordx4 v[196:197], off
	s_waitcnt vmcnt(8)
	s_waitcnt lgkmcnt(0)
	s_setprio 1
	s_barrier
	v_mfma_f32_16x16x32_bf16 v[8:11], v[136:139], v[180:183], v[8:11]
	v_mfma_f32_16x16x32_bf16 v[128:131], v[144:147], v[180:183], v[128:131]
	v_mfma_f32_16x16x32_bf16 v[124:127], v[136:139], v[188:191], v[124:127]
	v_mfma_f32_16x16x32_bf16 v[120:123], v[144:147], v[188:191], v[120:123]
	v_mfma_f32_16x16x32_bf16 v[116:119], v[136:139], v[212:215], v[116:119]
	v_mfma_f32_16x16x32_bf16 v[112:115], v[144:147], v[212:215], v[112:115]
	v_mfma_f32_16x16x32_bf16 v[108:111], v[136:139], v[230:233], v[108:111]
	v_mfma_f32_16x16x32_bf16 v[104:107], v[144:147], v[230:233], v[104:107]
	v_mfma_f32_16x16x32_bf16 v[8:11], v[140:143], v[184:187], v[8:11]
	v_mfma_f32_16x16x32_bf16 v[128:131], v[148:151], v[184:187], v[128:131]
	v_mfma_f32_16x16x32_bf16 v[124:127], v[140:143], v[192:195], v[124:127]
	v_mfma_f32_16x16x32_bf16 v[120:123], v[148:151], v[192:195], v[120:123]
	v_mfma_f32_16x16x32_bf16 v[116:119], v[140:143], v[226:229], v[116:119]
	v_mfma_f32_16x16x32_bf16 v[112:115], v[148:151], v[226:229], v[112:115]
	v_mfma_f32_16x16x32_bf16 v[108:111], v[140:143], v[234:237], v[108:111]
	v_mfma_f32_16x16x32_bf16 v[104:107], v[148:151], v[234:237], v[104:107]
	s_setprio 0
	s_setprio 1
	v_mfma_f32_16x16x32_bf16 v[100:103], v[152:155], v[180:183], v[100:103]
	v_mfma_f32_16x16x32_bf16 v[96:99], v[160:163], v[180:183], v[96:99]
	v_mfma_f32_16x16x32_bf16 v[92:95], v[152:155], v[188:191], v[92:95]
	v_mfma_f32_16x16x32_bf16 v[88:91], v[160:163], v[188:191], v[88:91]
	v_mfma_f32_16x16x32_bf16 v[84:87], v[152:155], v[212:215], v[84:87]
	v_mfma_f32_16x16x32_bf16 v[80:83], v[160:163], v[212:215], v[80:83]
	v_mfma_f32_16x16x32_bf16 v[76:79], v[152:155], v[230:233], v[76:79]
	v_mfma_f32_16x16x32_bf16 v[72:75], v[160:163], v[230:233], v[72:75]
	v_mfma_f32_16x16x32_bf16 v[100:103], v[156:159], v[184:187], v[100:103]
	v_mfma_f32_16x16x32_bf16 v[96:99], v[176:179], v[184:187], v[96:99]
	v_mfma_f32_16x16x32_bf16 v[92:95], v[156:159], v[192:195], v[92:95]
	v_mfma_f32_16x16x32_bf16 v[88:91], v[176:179], v[192:195], v[88:91]
	v_mfma_f32_16x16x32_bf16 v[84:87], v[156:159], v[226:229], v[84:87]
	v_mfma_f32_16x16x32_bf16 v[80:83], v[176:179], v[226:229], v[80:83]
	v_mfma_f32_16x16x32_bf16 v[76:79], v[156:159], v[234:237], v[76:79]
	v_mfma_f32_16x16x32_bf16 v[72:75], v[176:179], v[234:237], v[72:75]
	s_setprio 0
	s_barrier
	s_add_i32 s83, s95, s74
	v_lshl_add_u64 v[196:197], s[12:13], 0, v[164:165]
	s_mov_b32 m0, s83
	ds_read_b128 v[180:183], v209 offset:16384
	ds_read_b128 v[184:187], v209 offset:17408
	ds_read_b128 v[188:191], v209 offset:18432
	ds_read_b128 v[192:195], v209 offset:19456
	ds_read_b128 v[212:215], v209 offset:20480
	ds_read_b128 v[226:229], v209 offset:21504
	ds_read_b128 v[230:233], v209 offset:22528
	ds_read_b128 v[234:237], v209 offset:23552
	global_load_lds_dwordx4 v[196:197], off
	s_add_i32 m0, s83, 0x2000
	s_add_u32 vcc_lo, s12, 0x80000
	v_lshl_add_u64 v[198:199], s[12:13], 0, v[168:169]
	s_addc_u32 vcc_hi, s13, 0
	s_add_i32 s81, s81, s74
	global_load_lds_dwordx4 v[198:199], off
	v_lshl_add_u64 v[200:201], vcc, 0, v[164:165]
	s_mov_b32 m0, s81
	v_lshl_add_u64 v[202:203], s[36:37], 0, v[166:167]
	global_load_lds_dwordx4 v[200:201], off
	v_lshl_add_u64 v[200:201], vcc, 0, v[168:169]
	s_add_i32 m0, s81, 0x2000
	s_nop 0
	global_load_lds_dwordx4 v[200:201], off
	v_lshl_add_u64 v[200:201], s[36:37], 0, v[0:1]
	s_mov_b32 m0, s75
	s_nop 0
	global_load_lds_dwordx4 v[200:201], off
	s_mov_b32 m0, s15
	s_nop 0
	global_load_lds_dwordx4 v[202:203], off
	s_waitcnt vmcnt(8)
	s_waitcnt lgkmcnt(0)
	s_setprio 1
	s_barrier
	v_mfma_f32_16x16x32_bf16 v[68:71], v[136:139], v[180:183], v[68:71]
	v_mfma_f32_16x16x32_bf16 v[64:67], v[144:147], v[180:183], v[64:67]
	v_mfma_f32_16x16x32_bf16 v[60:63], v[136:139], v[188:191], v[60:63]
	v_mfma_f32_16x16x32_bf16 v[56:59], v[144:147], v[188:191], v[56:59]
	v_mfma_f32_16x16x32_bf16 v[52:55], v[136:139], v[212:215], v[52:55]
	v_mfma_f32_16x16x32_bf16 v[48:51], v[144:147], v[212:215], v[48:51]
	v_mfma_f32_16x16x32_bf16 v[44:47], v[136:139], v[230:233], v[44:47]
	v_mfma_f32_16x16x32_bf16 v[40:43], v[144:147], v[230:233], v[40:43]
	v_mfma_f32_16x16x32_bf16 v[68:71], v[140:143], v[184:187], v[68:71]
	v_mfma_f32_16x16x32_bf16 v[64:67], v[148:151], v[184:187], v[64:67]
	v_mfma_f32_16x16x32_bf16 v[60:63], v[140:143], v[192:195], v[60:63]
	v_mfma_f32_16x16x32_bf16 v[56:59], v[148:151], v[192:195], v[56:59]
	v_mfma_f32_16x16x32_bf16 v[52:55], v[140:143], v[226:229], v[52:55]
	v_mfma_f32_16x16x32_bf16 v[48:51], v[148:151], v[226:229], v[48:51]
	v_mfma_f32_16x16x32_bf16 v[44:47], v[140:143], v[234:237], v[44:47]
	v_mfma_f32_16x16x32_bf16 v[40:43], v[148:151], v[234:237], v[40:43]
	s_setprio 0
	s_setprio 1
	v_mfma_f32_16x16x32_bf16 v[36:39], v[152:155], v[180:183], v[36:39]
	v_mfma_f32_16x16x32_bf16 v[32:35], v[160:163], v[180:183], v[32:35]
	v_mfma_f32_16x16x32_bf16 v[28:31], v[152:155], v[188:191], v[28:31]
	v_mfma_f32_16x16x32_bf16 v[24:27], v[160:163], v[188:191], v[24:27]
	v_mfma_f32_16x16x32_bf16 v[20:23], v[152:155], v[212:215], v[20:23]
	v_mfma_f32_16x16x32_bf16 v[16:19], v[160:163], v[212:215], v[16:19]
	v_mfma_f32_16x16x32_bf16 v[12:15], v[152:155], v[230:233], v[12:15]
	v_mfma_f32_16x16x32_bf16 v[4:7], v[160:163], v[230:233], v[4:7]
	v_mfma_f32_16x16x32_bf16 v[36:39], v[156:159], v[184:187], v[36:39]
	v_mfma_f32_16x16x32_bf16 v[32:35], v[176:179], v[184:187], v[32:35]
	v_mfma_f32_16x16x32_bf16 v[28:31], v[156:159], v[192:195], v[28:31]
	v_mfma_f32_16x16x32_bf16 v[24:27], v[176:179], v[192:195], v[24:27]
	v_mfma_f32_16x16x32_bf16 v[20:23], v[156:159], v[226:229], v[20:23]
	v_mfma_f32_16x16x32_bf16 v[16:19], v[176:179], v[226:229], v[16:19]
	v_mfma_f32_16x16x32_bf16 v[12:15], v[156:159], v[234:237], v[12:15]
	v_mfma_f32_16x16x32_bf16 v[4:7], v[176:179], v[234:237], v[4:7]
	s_setprio 0
	s_barrier
	s_add_i32 s81, 0, 0x18000
	s_add_i32 s83, 0, 0x1c000
	v_add_u32_e32 v148, s81, v207
	v_add_u32_e32 v176, s83, v207
	ds_read_b128 v[136:139], v148
	ds_read_b128 v[140:143], v148 offset:1024
	ds_read_b128 v[144:147], v148 offset:2048
	ds_read_b128 v[148:151], v148 offset:3072
	ds_read_b128 v[152:155], v176
	ds_read_b128 v[156:159], v176 offset:1024
	ds_read_b128 v[160:163], v176 offset:2048
	ds_read_b128 v[176:179], v176 offset:3072
	s_add_u32 s36, s36, 0x80000
	s_addc_u32 s37, s37, 0
	s_mov_b32 m0, s38
	v_lshl_add_u64 v[216:217], s[36:37], 0, v[0:1]
	ds_read_b128 v[180:183], v209 offset:32768
	ds_read_b128 v[184:187], v209 offset:33792
	ds_read_b128 v[188:191], v209 offset:34816
	ds_read_b128 v[192:195], v209 offset:35840
	ds_read_b128 v[212:215], v209 offset:36864
	ds_read_b128 v[226:229], v209 offset:37888
	ds_read_b128 v[230:233], v209 offset:38912
	ds_read_b128 v[234:237], v209 offset:39936
	global_load_lds_dwordx4 v[216:217], off
	v_lshl_add_u64 v[216:217], s[36:37], 0, v[166:167]
	s_mov_b32 m0, s39
	s_nop 0
	global_load_lds_dwordx4 v[216:217], off
	s_waitcnt vmcnt(8)
	s_waitcnt lgkmcnt(0)
	s_setprio 1
	s_barrier
	v_mfma_f32_16x16x32_bf16 v[8:11], v[136:139], v[180:183], v[8:11]
	v_mfma_f32_16x16x32_bf16 v[128:131], v[144:147], v[180:183], v[128:131]
	v_mfma_f32_16x16x32_bf16 v[124:127], v[136:139], v[188:191], v[124:127]
	v_mfma_f32_16x16x32_bf16 v[120:123], v[144:147], v[188:191], v[120:123]
	v_mfma_f32_16x16x32_bf16 v[116:119], v[136:139], v[212:215], v[116:119]
	v_mfma_f32_16x16x32_bf16 v[112:115], v[144:147], v[212:215], v[112:115]
	v_mfma_f32_16x16x32_bf16 v[108:111], v[136:139], v[230:233], v[108:111]
	v_mfma_f32_16x16x32_bf16 v[104:107], v[144:147], v[230:233], v[104:107]
	v_mfma_f32_16x16x32_bf16 v[8:11], v[140:143], v[184:187], v[8:11]
	v_mfma_f32_16x16x32_bf16 v[128:131], v[148:151], v[184:187], v[128:131]
	v_mfma_f32_16x16x32_bf16 v[124:127], v[140:143], v[192:195], v[124:127]
	v_mfma_f32_16x16x32_bf16 v[120:123], v[148:151], v[192:195], v[120:123]
	v_mfma_f32_16x16x32_bf16 v[116:119], v[140:143], v[226:229], v[116:119]
	v_mfma_f32_16x16x32_bf16 v[112:115], v[148:151], v[226:229], v[112:115]
	v_mfma_f32_16x16x32_bf16 v[108:111], v[140:143], v[234:237], v[108:111]
	v_mfma_f32_16x16x32_bf16 v[104:107], v[148:151], v[234:237], v[104:107]
	s_setprio 0
	s_setprio 1
	v_mfma_f32_16x16x32_bf16 v[100:103], v[152:155], v[180:183], v[100:103]
	v_mfma_f32_16x16x32_bf16 v[96:99], v[160:163], v[180:183], v[96:99]
	v_mfma_f32_16x16x32_bf16 v[92:95], v[152:155], v[188:191], v[92:95]
	v_mfma_f32_16x16x32_bf16 v[88:91], v[160:163], v[188:191], v[88:91]
	v_mfma_f32_16x16x32_bf16 v[84:87], v[152:155], v[212:215], v[84:87]
	v_mfma_f32_16x16x32_bf16 v[80:83], v[160:163], v[212:215], v[80:83]
	v_mfma_f32_16x16x32_bf16 v[76:79], v[152:155], v[230:233], v[76:79]
	v_mfma_f32_16x16x32_bf16 v[72:75], v[160:163], v[230:233], v[72:75]
	v_mfma_f32_16x16x32_bf16 v[100:103], v[156:159], v[184:187], v[100:103]
	v_mfma_f32_16x16x32_bf16 v[96:99], v[176:179], v[184:187], v[96:99]
	v_mfma_f32_16x16x32_bf16 v[92:95], v[156:159], v[192:195], v[92:95]
	v_mfma_f32_16x16x32_bf16 v[88:91], v[176:179], v[192:195], v[88:91]
	v_mfma_f32_16x16x32_bf16 v[84:87], v[156:159], v[226:229], v[84:87]
	v_mfma_f32_16x16x32_bf16 v[80:83], v[176:179], v[226:229], v[80:83]
	v_mfma_f32_16x16x32_bf16 v[76:79], v[156:159], v[234:237], v[76:79]
	v_mfma_f32_16x16x32_bf16 v[72:75], v[176:179], v[234:237], v[72:75]
	s_setprio 0
	s_barrier
	s_add_i32 s36, s81, s74
	v_lshl_add_u64 v[196:197], v[196:197], 0, s[70:71]
	s_mov_b32 m0, s36
	ds_read_b128 v[180:183], v209 offset:49152
	ds_read_b128 v[184:187], v209 offset:50176
	ds_read_b128 v[188:191], v209 offset:51200
	ds_read_b128 v[192:195], v209 offset:52224
	ds_read_b128 v[212:215], v209 offset:53248
	ds_read_b128 v[226:229], v209 offset:54272
	ds_read_b128 v[230:233], v209 offset:55296
	ds_read_b128 v[234:237], v209 offset:56320
	global_load_lds_dwordx4 v[196:197], off
	s_add_i32 m0, s36, 0x2000
	s_add_u32 s12, s12, 0x80080
	v_lshl_add_u64 v[196:197], v[198:199], 0, s[70:71]
	s_addc_u32 s13, s13, 0
	s_add_i32 s36, s83, s74
	global_load_lds_dwordx4 v[196:197], off
	v_lshl_add_u64 v[196:197], s[12:13], 0, v[164:165]
	s_mov_b32 m0, s36
	s_nop 0
	global_load_lds_dwordx4 v[196:197], off
	v_lshl_add_u64 v[196:197], s[12:13], 0, v[168:169]
	s_add_i32 m0, s36, 0x2000
	s_nop 0
	global_load_lds_dwordx4 v[196:197], off
	v_lshl_add_u64 v[196:197], v[200:201], 0, s[70:71]
	s_mov_b32 m0, s51
	s_nop 0
	global_load_lds_dwordx4 v[196:197], off
	v_lshl_add_u64 v[196:197], v[202:203], 0, s[70:71]
	s_mov_b32 m0, s92
	s_nop 0
	global_load_lds_dwordx4 v[196:197], off
	s_waitcnt vmcnt(8)
	s_waitcnt lgkmcnt(0)
	s_setprio 1
	s_barrier
	v_mfma_f32_16x16x32_bf16 v[68:71], v[136:139], v[180:183], v[68:71]
	v_mfma_f32_16x16x32_bf16 v[64:67], v[144:147], v[180:183], v[64:67]
	v_mfma_f32_16x16x32_bf16 v[60:63], v[136:139], v[188:191], v[60:63]
	v_mfma_f32_16x16x32_bf16 v[56:59], v[144:147], v[188:191], v[56:59]
	v_mfma_f32_16x16x32_bf16 v[52:55], v[136:139], v[212:215], v[52:55]
	v_mfma_f32_16x16x32_bf16 v[48:51], v[144:147], v[212:215], v[48:51]
	v_mfma_f32_16x16x32_bf16 v[44:47], v[136:139], v[230:233], v[44:47]
	v_mfma_f32_16x16x32_bf16 v[40:43], v[144:147], v[230:233], v[40:43]
	v_mfma_f32_16x16x32_bf16 v[68:71], v[140:143], v[184:187], v[68:71]
	v_mfma_f32_16x16x32_bf16 v[64:67], v[148:151], v[184:187], v[64:67]
	v_mfma_f32_16x16x32_bf16 v[60:63], v[140:143], v[192:195], v[60:63]
	v_mfma_f32_16x16x32_bf16 v[56:59], v[148:151], v[192:195], v[56:59]
	v_mfma_f32_16x16x32_bf16 v[52:55], v[140:143], v[226:229], v[52:55]
	v_mfma_f32_16x16x32_bf16 v[48:51], v[148:151], v[226:229], v[48:51]
	v_mfma_f32_16x16x32_bf16 v[44:47], v[140:143], v[234:237], v[44:47]
	v_mfma_f32_16x16x32_bf16 v[40:43], v[148:151], v[234:237], v[40:43]
	s_setprio 0
	s_setprio 1
	v_mfma_f32_16x16x32_bf16 v[36:39], v[152:155], v[180:183], v[36:39]
	v_mfma_f32_16x16x32_bf16 v[32:35], v[160:163], v[180:183], v[32:35]
	v_mfma_f32_16x16x32_bf16 v[28:31], v[152:155], v[188:191], v[28:31]
	v_mfma_f32_16x16x32_bf16 v[24:27], v[160:163], v[188:191], v[24:27]
	v_mfma_f32_16x16x32_bf16 v[20:23], v[152:155], v[212:215], v[20:23]
	v_mfma_f32_16x16x32_bf16 v[16:19], v[160:163], v[212:215], v[16:19]
	v_mfma_f32_16x16x32_bf16 v[12:15], v[152:155], v[230:233], v[12:15]
	v_mfma_f32_16x16x32_bf16 v[4:7], v[160:163], v[230:233], v[4:7]
	v_mfma_f32_16x16x32_bf16 v[36:39], v[156:159], v[184:187], v[36:39]
	v_mfma_f32_16x16x32_bf16 v[32:35], v[176:179], v[184:187], v[32:35]
	v_mfma_f32_16x16x32_bf16 v[28:31], v[156:159], v[192:195], v[28:31]
	v_mfma_f32_16x16x32_bf16 v[24:27], v[176:179], v[192:195], v[24:27]
	v_mfma_f32_16x16x32_bf16 v[20:23], v[156:159], v[226:229], v[20:23]
	v_mfma_f32_16x16x32_bf16 v[16:19], v[176:179], v[226:229], v[16:19]
	v_mfma_f32_16x16x32_bf16 v[12:15], v[156:159], v[234:237], v[12:15]
	v_mfma_f32_16x16x32_bf16 v[4:7], v[176:179], v[234:237], v[4:7]
	s_setprio 0
	s_barrier
	s_add_i32 s52, s52, 2
	s_add_u32 s8, s8, 0x100
	s_addc_u32 s9, s9, 0
	s_cmp_gt_u32 s52, 29
	s_cbranch_scc0 .LBB0_803
	s_and_b64 vcc, exec, s[22:23]
	s_cbranch_vccz .LBB0_806
	s_barrier

.LBB0_975:
	v_add_u32_e32 v144, 0x10000, v182
	v_add_u32_e32 v170, 0x14000, v182
	ds_read_b128 v[132:135], v144
	ds_read_b128 v[136:139], v144 offset:1024
	ds_read_b128 v[140:143], v144 offset:2048
	ds_read_b128 v[144:147], v144 offset:3072
	ds_read_b128 v[148:151], v170
	ds_read_b128 v[152:155], v170 offset:1024
	ds_read_b128 v[156:159], v170 offset:2048
	ds_read_b128 v[170:173], v170 offset:3072
	v_lshl_add_u64 v[212:213], s[30:31], 0, v[166:167]
	s_add_i32 m0, s15, 0xc000
	ds_read_b128 v[174:177], v186
	ds_read_b128 v[178:181], v186 offset:1024
	ds_read_b128 v[188:191], v186 offset:2048
	ds_read_b128 v[192:195], v186 offset:3072
	ds_read_b128 v[196:199], v186 offset:4096
	ds_read_b128 v[200:203], v186 offset:5120
	ds_read_b128 v[204:207], v186 offset:6144
	ds_read_b128 v[208:211], v186 offset:7168
	s_add_u32 s34, s30, 0xfff80080
	s_addc_u32 s35, s31, -1
	s_add_i32 s81, 0, 0x10000
	s_cmp_eq_u32 s75, 28
	s_cselect_b32 s37, s25, s35
	s_cselect_b32 s36, s66, s34
	s_cselect_b32 s35, s23, s74
	s_cselect_b32 s34, s67, s69
	s_add_i32 s83, 0, 0x14000
	global_load_lds_dwordx4 v[212:213], off
	v_lshl_add_u64 v[212:213], s[30:31], 0, v[168:169]
	s_add_i32 m0, s15, 0xe000
	s_nop 0
	global_load_lds_dwordx4 v[212:213], off
	s_waitcnt vmcnt(8)
	s_waitcnt lgkmcnt(0)
	s_setprio 1
	s_barrier
	v_mfma_f32_16x16x32_bf16 v[128:131], v[132:135], v[174:177], v[128:131]
	v_mfma_f32_16x16x32_bf16 v[124:127], v[140:143], v[174:177], v[124:127]
	v_mfma_f32_16x16x32_bf16 v[112:115], v[132:135], v[188:191], v[112:115]
	v_mfma_f32_16x16x32_bf16 v[108:111], v[140:143], v[188:191], v[108:111]
	v_mfma_f32_16x16x32_bf16 v[96:99], v[132:135], v[196:199], v[96:99]
	v_mfma_f32_16x16x32_bf16 v[92:95], v[140:143], v[196:199], v[92:95]
	v_mfma_f32_16x16x32_bf16 v[80:83], v[132:135], v[204:207], v[80:83]
	v_mfma_f32_16x16x32_bf16 v[76:79], v[140:143], v[204:207], v[76:79]
	v_mfma_f32_16x16x32_bf16 v[128:131], v[136:139], v[178:181], v[128:131]
	v_mfma_f32_16x16x32_bf16 v[124:127], v[144:147], v[178:181], v[124:127]
	v_mfma_f32_16x16x32_bf16 v[112:115], v[136:139], v[192:195], v[112:115]
	v_mfma_f32_16x16x32_bf16 v[108:111], v[144:147], v[192:195], v[108:111]
	v_mfma_f32_16x16x32_bf16 v[96:99], v[136:139], v[200:203], v[96:99]
	v_mfma_f32_16x16x32_bf16 v[92:95], v[144:147], v[200:203], v[92:95]
	v_mfma_f32_16x16x32_bf16 v[80:83], v[136:139], v[208:211], v[80:83]
	v_mfma_f32_16x16x32_bf16 v[76:79], v[144:147], v[208:211], v[76:79]
	s_setprio 0
	s_setprio 1
	v_mfma_f32_16x16x32_bf16 v[120:123], v[148:151], v[174:177], v[120:123]
	v_mfma_f32_16x16x32_bf16 v[116:119], v[156:159], v[174:177], v[116:119]
	v_mfma_f32_16x16x32_bf16 v[104:107], v[148:151], v[188:191], v[104:107]
	v_mfma_f32_16x16x32_bf16 v[100:103], v[156:159], v[188:191], v[100:103]
	v_mfma_f32_16x16x32_bf16 v[88:91], v[148:151], v[196:199], v[88:91]
	v_mfma_f32_16x16x32_bf16 v[84:87], v[156:159], v[196:199], v[84:87]
	v_mfma_f32_16x16x32_bf16 v[72:75], v[148:151], v[204:207], v[72:75]
	v_mfma_f32_16x16x32_bf16 v[68:71], v[156:159], v[204:207], v[68:71]
	v_mfma_f32_16x16x32_bf16 v[120:123], v[152:155], v[178:181], v[120:123]
	v_mfma_f32_16x16x32_bf16 v[116:119], v[170:173], v[178:181], v[116:119]
	v_mfma_f32_16x16x32_bf16 v[104:107], v[152:155], v[192:195], v[104:107]
	v_mfma_f32_16x16x32_bf16 v[100:103], v[170:173], v[192:195], v[100:103]
	v_mfma_f32_16x16x32_bf16 v[88:91], v[152:155], v[200:203], v[88:91]
	v_mfma_f32_16x16x32_bf16 v[84:87], v[170:173], v[200:203], v[84:87]
	v_mfma_f32_16x16x32_bf16 v[72:75], v[152:155], v[208:211], v[72:75]
	v_mfma_f32_16x16x32_bf16 v[68:71], v[170:173], v[208:211], v[68:71]
	s_setprio 0
	s_barrier
	s_add_i32 s81, s81, s0
	v_lshl_add_u64 v[212:213], s[34:35], 0, v[162:163]
	s_mov_b32 m0, s81
	ds_read_b128 v[174:177], v186 offset:16384
	ds_read_b128 v[178:181], v186 offset:17408
	ds_read_b128 v[188:191], v186 offset:18432
	ds_read_b128 v[192:195], v186 offset:19456
	ds_read_b128 v[196:199], v186 offset:20480
	ds_read_b128 v[200:203], v186 offset:21504
	ds_read_b128 v[204:207], v186 offset:22528
	ds_read_b128 v[208:211], v186 offset:23552
	global_load_lds_dwordx4 v[212:213], off
	s_add_i32 m0, s81, 0x2000
	s_add_u32 s84, s34, 0x80000
	v_lshl_add_u64 v[214:215], s[34:35], 0, v[0:1]
	s_addc_u32 s85, s35, 0
	s_add_i32 s81, s83, s0
	global_load_lds_dwordx4 v[214:215], off
	v_lshl_add_u64 v[216:217], s[84:85], 0, v[162:163]
	s_mov_b32 m0, s81
	v_lshl_add_u64 v[226:227], s[36:37], 0, v[160:161]
	global_load_lds_dwordx4 v[216:217], off
	v_lshl_add_u64 v[216:217], s[84:85], 0, v[0:1]
	s_add_i32 m0, s81, 0x2000
	s_nop 0
	global_load_lds_dwordx4 v[216:217], off
	v_lshl_add_u64 v[216:217], s[36:37], 0, v[164:165]
	s_mov_b32 m0, s15
	s_nop 0
	global_load_lds_dwordx4 v[216:217], off
	s_mov_b32 m0, s38
	s_nop 0
	global_load_lds_dwordx4 v[226:227], off
	s_waitcnt vmcnt(8)
	s_waitcnt lgkmcnt(0)
	s_setprio 1
	s_barrier
	v_mfma_f32_16x16x32_bf16 v[64:67], v[132:135], v[174:177], v[64:67]
	v_mfma_f32_16x16x32_bf16 v[60:63], v[140:143], v[174:177], v[60:63]
	v_mfma_f32_16x16x32_bf16 v[48:51], v[132:135], v[188:191], v[48:51]
	v_mfma_f32_16x16x32_bf16 v[44:47], v[140:143], v[188:191], v[44:47]
	v_mfma_f32_16x16x32_bf16 v[32:35], v[132:135], v[196:199], v[32:35]
	v_mfma_f32_16x16x32_bf16 v[28:31], v[140:143], v[196:199], v[28:31]
	v_mfma_f32_16x16x32_bf16 v[16:19], v[132:135], v[204:207], v[16:19]
	v_mfma_f32_16x16x32_bf16 v[12:15], v[140:143], v[204:207], v[12:15]
	v_mfma_f32_16x16x32_bf16 v[64:67], v[136:139], v[178:181], v[64:67]
	v_mfma_f32_16x16x32_bf16 v[60:63], v[144:147], v[178:181], v[60:63]
	v_mfma_f32_16x16x32_bf16 v[48:51], v[136:139], v[192:195], v[48:51]
	v_mfma_f32_16x16x32_bf16 v[44:47], v[144:147], v[192:195], v[44:47]
	v_mfma_f32_16x16x32_bf16 v[32:35], v[136:139], v[200:203], v[32:35]
	v_mfma_f32_16x16x32_bf16 v[28:31], v[144:147], v[200:203], v[28:31]
	v_mfma_f32_16x16x32_bf16 v[16:19], v[136:139], v[208:211], v[16:19]
	v_mfma_f32_16x16x32_bf16 v[12:15], v[144:147], v[208:211], v[12:15]
	s_setprio 0
	s_setprio 1
	v_mfma_f32_16x16x32_bf16 v[56:59], v[148:151], v[174:177], v[56:59]
	v_mfma_f32_16x16x32_bf16 v[52:55], v[156:159], v[174:177], v[52:55]
	v_mfma_f32_16x16x32_bf16 v[40:43], v[148:151], v[188:191], v[40:43]
	v_mfma_f32_16x16x32_bf16 v[36:39], v[156:159], v[188:191], v[36:39]
	v_mfma_f32_16x16x32_bf16 v[24:27], v[148:151], v[196:199], v[24:27]
	v_mfma_f32_16x16x32_bf16 v[20:23], v[156:159], v[196:199], v[20:23]
	v_mfma_f32_16x16x32_bf16 v[8:11], v[148:151], v[204:207], v[8:11]
	v_mfma_f32_16x16x32_bf16 v[4:7], v[156:159], v[204:207], v[4:7]
	v_mfma_f32_16x16x32_bf16 v[56:59], v[152:155], v[178:181], v[56:59]
	v_mfma_f32_16x16x32_bf16 v[52:55], v[170:173], v[178:181], v[52:55]
	v_mfma_f32_16x16x32_bf16 v[40:43], v[152:155], v[192:195], v[40:43]
	v_mfma_f32_16x16x32_bf16 v[36:39], v[170:173], v[192:195], v[36:39]
	v_mfma_f32_16x16x32_bf16 v[24:27], v[152:155], v[200:203], v[24:27]
	v_mfma_f32_16x16x32_bf16 v[20:23], v[170:173], v[200:203], v[20:23]
	v_mfma_f32_16x16x32_bf16 v[8:11], v[152:155], v[208:211], v[8:11]
	v_mfma_f32_16x16x32_bf16 v[4:7], v[170:173], v[208:211], v[4:7]
	s_setprio 0
	s_barrier
	s_add_i32 s81, 0, 0x18000
	s_add_i32 s83, 0, 0x1c000
	v_add_u32_e32 v144, s81, v182
	v_add_u32_e32 v170, s83, v182
	ds_read_b128 v[132:135], v144
	ds_read_b128 v[136:139], v144 offset:1024
	ds_read_b128 v[140:143], v144 offset:2048
	ds_read_b128 v[144:147], v144 offset:3072
	ds_read_b128 v[148:151], v170
	ds_read_b128 v[152:155], v170 offset:1024
	ds_read_b128 v[156:159], v170 offset:2048
	ds_read_b128 v[170:173], v170 offset:3072
	s_add_u32 s36, s36, 0x80000
	s_addc_u32 s37, s37, 0
	s_mov_b32 m0, s39
	v_lshl_add_u64 v[228:229], s[36:37], 0, v[164:165]
	ds_read_b128 v[174:177], v186 offset:32768
	ds_read_b128 v[178:181], v186 offset:33792
	ds_read_b128 v[188:191], v186 offset:34816
	ds_read_b128 v[192:195], v186 offset:35840
	ds_read_b128 v[196:199], v186 offset:36864
	ds_read_b128 v[200:203], v186 offset:37888
	ds_read_b128 v[204:207], v186 offset:38912
	ds_read_b128 v[208:211], v186 offset:39936
	global_load_lds_dwordx4 v[228:229], off
	v_lshl_add_u64 v[228:229], s[36:37], 0, v[160:161]
	s_mov_b32 m0, s43
	s_nop 0
	global_load_lds_dwordx4 v[228:229], off
	s_waitcnt vmcnt(8)
	s_waitcnt lgkmcnt(0)
	s_setprio 1
	s_barrier
	v_mfma_f32_16x16x32_bf16 v[128:131], v[132:135], v[174:177], v[128:131]
	v_mfma_f32_16x16x32_bf16 v[124:127], v[140:143], v[174:177], v[124:127]
	v_mfma_f32_16x16x32_bf16 v[112:115], v[132:135], v[188:191], v[112:115]
	v_mfma_f32_16x16x32_bf16 v[108:111], v[140:143], v[188:191], v[108:111]
	v_mfma_f32_16x16x32_bf16 v[96:99], v[132:135], v[196:199], v[96:99]
	v_mfma_f32_16x16x32_bf16 v[92:95], v[140:143], v[196:199], v[92:95]
	v_mfma_f32_16x16x32_bf16 v[80:83], v[132:135], v[204:207], v[80:83]
	v_mfma_f32_16x16x32_bf16 v[76:79], v[140:143], v[204:207], v[76:79]
	v_mfma_f32_16x16x32_bf16 v[128:131], v[136:139], v[178:181], v[128:131]
	v_mfma_f32_16x16x32_bf16 v[124:127], v[144:147], v[178:181], v[124:127]
	v_mfma_f32_16x16x32_bf16 v[112:115], v[136:139], v[192:195], v[112:115]
	v_mfma_f32_16x16x32_bf16 v[108:111], v[144:147], v[192:195], v[108:111]
	v_mfma_f32_16x16x32_bf16 v[96:99], v[136:139], v[200:203], v[96:99]
	v_mfma_f32_16x16x32_bf16 v[92:95], v[144:147], v[200:203], v[92:95]
	v_mfma_f32_16x16x32_bf16 v[80:83], v[136:139], v[208:211], v[80:83]
	v_mfma_f32_16x16x32_bf16 v[76:79], v[144:147], v[208:211], v[76:79]
	s_setprio 0
	s_setprio 1
	v_mfma_f32_16x16x32_bf16 v[120:123], v[148:151], v[174:177], v[120:123]
	v_mfma_f32_16x16x32_bf16 v[116:119], v[156:159], v[174:177], v[116:119]
	v_mfma_f32_16x16x32_bf16 v[104:107], v[148:151], v[188:191], v[104:107]
	v_mfma_f32_16x16x32_bf16 v[100:103], v[156:159], v[188:191], v[100:103]
	v_mfma_f32_16x16x32_bf16 v[88:91], v[148:151], v[196:199], v[88:91]
	v_mfma_f32_16x16x32_bf16 v[84:87], v[156:159], v[196:199], v[84:87]
	v_mfma_f32_16x16x32_bf16 v[72:75], v[148:151], v[204:207], v[72:75]
	v_mfma_f32_16x16x32_bf16 v[68:71], v[156:159], v[204:207], v[68:71]
	v_mfma_f32_16x16x32_bf16 v[120:123], v[152:155], v[178:181], v[120:123]
	v_mfma_f32_16x16x32_bf16 v[116:119], v[170:173], v[178:181], v[116:119]
	v_mfma_f32_16x16x32_bf16 v[104:107], v[152:155], v[192:195], v[104:107]
	v_mfma_f32_16x16x32_bf16 v[100:103], v[170:173], v[192:195], v[100:103]
	v_mfma_f32_16x16x32_bf16 v[88:91], v[152:155], v[200:203], v[88:91]
	v_mfma_f32_16x16x32_bf16 v[84:87], v[170:173], v[200:203], v[84:87]
	v_mfma_f32_16x16x32_bf16 v[72:75], v[152:155], v[208:211], v[72:75]
	v_mfma_f32_16x16x32_bf16 v[68:71], v[170:173], v[208:211], v[68:71]
	s_setprio 0
	s_barrier
	s_add_i32 s36, s81, s0
	v_lshl_add_u64 v[212:213], v[212:213], 0, s[70:71]
	s_mov_b32 m0, s36
	ds_read_b128 v[174:177], v186 offset:49152
	ds_read_b128 v[178:181], v186 offset:50176
	ds_read_b128 v[188:191], v186 offset:51200
	ds_read_b128 v[192:195], v186 offset:52224
	ds_read_b128 v[196:199], v186 offset:53248
	ds_read_b128 v[200:203], v186 offset:54272
	ds_read_b128 v[204:207], v186 offset:55296
	ds_read_b128 v[208:211], v186 offset:56320
	global_load_lds_dwordx4 v[212:213], off
	s_add_i32 m0, s36, 0x2000
	s_add_u32 s34, s34, 0x80080
	v_lshl_add_u64 v[212:213], v[214:215], 0, s[70:71]
	s_addc_u32 s35, s35, 0
	s_add_i32 s36, s83, s0
	global_load_lds_dwordx4 v[212:213], off
	v_lshl_add_u64 v[212:213], s[34:35], 0, v[162:163]
	s_mov_b32 m0, s36
	s_nop 0
	global_load_lds_dwordx4 v[212:213], off
	v_lshl_add_u64 v[212:213], s[34:35], 0, v[0:1]
	s_add_i32 m0, s36, 0x2000
	s_nop 0
	global_load_lds_dwordx4 v[212:213], off
	v_lshl_add_u64 v[212:213], v[216:217], 0, s[70:71]
	s_mov_b32 m0, s47
	s_nop 0
	global_load_lds_dwordx4 v[212:213], off
	v_lshl_add_u64 v[212:213], v[226:227], 0, s[70:71]
	s_mov_b32 m0, s51
	s_nop 0
	global_load_lds_dwordx4 v[212:213], off
	s_waitcnt vmcnt(8)
	s_waitcnt lgkmcnt(0)
	s_setprio 1
	s_barrier
	v_mfma_f32_16x16x32_bf16 v[64:67], v[132:135], v[174:177], v[64:67]
	v_mfma_f32_16x16x32_bf16 v[60:63], v[140:143], v[174:177], v[60:63]
	v_mfma_f32_16x16x32_bf16 v[48:51], v[132:135], v[188:191], v[48:51]
	v_mfma_f32_16x16x32_bf16 v[44:47], v[140:143], v[188:191], v[44:47]
	v_mfma_f32_16x16x32_bf16 v[32:35], v[132:135], v[196:199], v[32:35]
	v_mfma_f32_16x16x32_bf16 v[28:31], v[140:143], v[196:199], v[28:31]
	v_mfma_f32_16x16x32_bf16 v[16:19], v[132:135], v[204:207], v[16:19]
	v_mfma_f32_16x16x32_bf16 v[12:15], v[140:143], v[204:207], v[12:15]
	v_mfma_f32_16x16x32_bf16 v[64:67], v[136:139], v[178:181], v[64:67]
	v_mfma_f32_16x16x32_bf16 v[60:63], v[144:147], v[178:181], v[60:63]
	v_mfma_f32_16x16x32_bf16 v[48:51], v[136:139], v[192:195], v[48:51]
	v_mfma_f32_16x16x32_bf16 v[44:47], v[144:147], v[192:195], v[44:47]
	v_mfma_f32_16x16x32_bf16 v[32:35], v[136:139], v[200:203], v[32:35]
	v_mfma_f32_16x16x32_bf16 v[28:31], v[144:147], v[200:203], v[28:31]
	v_mfma_f32_16x16x32_bf16 v[16:19], v[136:139], v[208:211], v[16:19]
	v_mfma_f32_16x16x32_bf16 v[12:15], v[144:147], v[208:211], v[12:15]
	s_setprio 0
	s_setprio 1
	v_mfma_f32_16x16x32_bf16 v[56:59], v[148:151], v[174:177], v[56:59]
	v_mfma_f32_16x16x32_bf16 v[52:55], v[156:159], v[174:177], v[52:55]
	v_mfma_f32_16x16x32_bf16 v[40:43], v[148:151], v[188:191], v[40:43]
	v_mfma_f32_16x16x32_bf16 v[36:39], v[156:159], v[188:191], v[36:39]
	v_mfma_f32_16x16x32_bf16 v[24:27], v[148:151], v[196:199], v[24:27]
	v_mfma_f32_16x16x32_bf16 v[20:23], v[156:159], v[196:199], v[20:23]
	v_mfma_f32_16x16x32_bf16 v[8:11], v[148:151], v[204:207], v[8:11]
	v_mfma_f32_16x16x32_bf16 v[4:7], v[156:159], v[204:207], v[4:7]
	v_mfma_f32_16x16x32_bf16 v[56:59], v[152:155], v[178:181], v[56:59]
	v_mfma_f32_16x16x32_bf16 v[52:55], v[170:173], v[178:181], v[52:55]
	v_mfma_f32_16x16x32_bf16 v[40:43], v[152:155], v[192:195], v[40:43]
	v_mfma_f32_16x16x32_bf16 v[36:39], v[170:173], v[192:195], v[36:39]
	v_mfma_f32_16x16x32_bf16 v[24:27], v[152:155], v[200:203], v[24:27]
	v_mfma_f32_16x16x32_bf16 v[20:23], v[170:173], v[200:203], v[20:23]
	v_mfma_f32_16x16x32_bf16 v[8:11], v[152:155], v[208:211], v[8:11]
	v_mfma_f32_16x16x32_bf16 v[4:7], v[170:173], v[208:211], v[4:7]
	s_setprio 0
	s_barrier
	s_add_i32 s75, s75, 2
	s_add_u32 s30, s30, 0x100
	s_addc_u32 s31, s31, 0
	s_add_u32 s69, s69, 0x100
	s_addc_u32 s74, s74, 0
	s_cmp_gt_u32 s75, 29
	s_cbranch_scc0 .LBB0_975
	s_and_b64 vcc, exec, s[20:21]
	s_cbranch_vccz .LBB0_978
	s_barrier

.LBB0_1067:
	v_add_u32_e32 v148, 0x10000, v189
	v_add_u32_e32 v176, 0x14000, v189
	ds_read_b128 v[136:139], v148
	ds_read_b128 v[140:143], v148 offset:1024
	ds_read_b128 v[144:147], v148 offset:2048
	ds_read_b128 v[148:151], v148 offset:3072
	ds_read_b128 v[152:155], v176
	ds_read_b128 v[156:159], v176 offset:1024
	ds_read_b128 v[160:163], v176 offset:2048
	ds_read_b128 v[176:179], v176 offset:3072
	v_lshl_add_u64 v[184:185], v[132:133], 0, s[12:13]
	s_add_i32 m0, s39, 0xc000
	ds_read_b128 v[180:183], v192
	ds_read_b128 v[194:197], v192 offset:1024
	ds_read_b128 v[198:201], v192 offset:2048
	ds_read_b128 v[202:205], v192 offset:3072
	ds_read_b128 v[206:209], v192 offset:4096
	ds_read_b128 v[210:213], v192 offset:5120
	ds_read_b128 v[214:217], v192 offset:6144
	ds_read_b128 v[226:229], v192 offset:7168
	s_add_u32 s34, s26, s12
	s_addc_u32 s35, s27, s13
	s_add_u32 s34, s34, 0x100
	s_addc_u32 s35, s35, 0
	s_add_u32 s83, s42, s12
	s_addc_u32 s92, s75, s13
	s_add_i32 s93, 0, 0x10000
	s_cmpk_eq_i32 s12, 0xf00
	s_cselect_b32 s37, s25, s35
	s_cselect_b32 s36, s81, s34
	s_cselect_b32 s35, s23, s92
	s_cselect_b32 s34, s84, s83
	s_add_i32 s83, 0, 0x14000
	global_load_lds_dwordx4 v[184:185], off
	v_lshl_add_u64 v[184:185], v[134:135], 0, s[12:13]
	s_add_i32 m0, s39, 0xe000
	s_nop 0
	global_load_lds_dwordx4 v[184:185], off
	s_waitcnt vmcnt(8)
	s_waitcnt lgkmcnt(0)
	s_setprio 1
	s_barrier
	v_mfma_f32_16x16x32_bf16 v[8:11], v[136:139], v[180:183], v[8:11]
	v_mfma_f32_16x16x32_bf16 v[128:131], v[144:147], v[180:183], v[128:131]
	v_mfma_f32_16x16x32_bf16 v[124:127], v[136:139], v[198:201], v[124:127]
	v_mfma_f32_16x16x32_bf16 v[120:123], v[144:147], v[198:201], v[120:123]
	v_mfma_f32_16x16x32_bf16 v[116:119], v[136:139], v[206:209], v[116:119]
	v_mfma_f32_16x16x32_bf16 v[112:115], v[144:147], v[206:209], v[112:115]
	v_mfma_f32_16x16x32_bf16 v[108:111], v[136:139], v[214:217], v[108:111]
	v_mfma_f32_16x16x32_bf16 v[104:107], v[144:147], v[214:217], v[104:107]
	v_mfma_f32_16x16x32_bf16 v[8:11], v[140:143], v[194:197], v[8:11]
	v_mfma_f32_16x16x32_bf16 v[128:131], v[148:151], v[194:197], v[128:131]
	v_mfma_f32_16x16x32_bf16 v[124:127], v[140:143], v[202:205], v[124:127]
	v_mfma_f32_16x16x32_bf16 v[120:123], v[148:151], v[202:205], v[120:123]
	v_mfma_f32_16x16x32_bf16 v[116:119], v[140:143], v[210:213], v[116:119]
	v_mfma_f32_16x16x32_bf16 v[112:115], v[148:151], v[210:213], v[112:115]
	v_mfma_f32_16x16x32_bf16 v[108:111], v[140:143], v[226:229], v[108:111]
	v_mfma_f32_16x16x32_bf16 v[104:107], v[148:151], v[226:229], v[104:107]
	s_setprio 0
	s_setprio 1
	v_mfma_f32_16x16x32_bf16 v[100:103], v[152:155], v[180:183], v[100:103]
	v_mfma_f32_16x16x32_bf16 v[96:99], v[160:163], v[180:183], v[96:99]
	v_mfma_f32_16x16x32_bf16 v[92:95], v[152:155], v[198:201], v[92:95]
	v_mfma_f32_16x16x32_bf16 v[88:91], v[160:163], v[198:201], v[88:91]
	v_mfma_f32_16x16x32_bf16 v[84:87], v[152:155], v[206:209], v[84:87]
	v_mfma_f32_16x16x32_bf16 v[80:83], v[160:163], v[206:209], v[80:83]
	v_mfma_f32_16x16x32_bf16 v[76:79], v[152:155], v[214:217], v[76:79]
	v_mfma_f32_16x16x32_bf16 v[72:75], v[160:163], v[214:217], v[72:75]
	v_mfma_f32_16x16x32_bf16 v[100:103], v[156:159], v[194:197], v[100:103]
	v_mfma_f32_16x16x32_bf16 v[96:99], v[176:179], v[194:197], v[96:99]
	v_mfma_f32_16x16x32_bf16 v[92:95], v[156:159], v[202:205], v[92:95]
	v_mfma_f32_16x16x32_bf16 v[88:91], v[176:179], v[202:205], v[88:91]
	v_mfma_f32_16x16x32_bf16 v[84:87], v[156:159], v[210:213], v[84:87]
	v_mfma_f32_16x16x32_bf16 v[80:83], v[176:179], v[210:213], v[80:83]
	v_mfma_f32_16x16x32_bf16 v[76:79], v[156:159], v[226:229], v[76:79]
	v_mfma_f32_16x16x32_bf16 v[72:75], v[176:179], v[226:229], v[72:75]
	s_setprio 0
	s_barrier
	s_add_i32 s92, s93, s38
	v_lshl_add_u64 v[184:185], s[34:35], 0, v[164:165]
	s_mov_b32 m0, s92
	ds_read_b128 v[180:183], v192 offset:16384
	ds_read_b128 v[194:197], v192 offset:17408
	ds_read_b128 v[198:201], v192 offset:18432
	ds_read_b128 v[202:205], v192 offset:19456
	ds_read_b128 v[206:209], v192 offset:20480
	ds_read_b128 v[210:213], v192 offset:21504
	ds_read_b128 v[214:217], v192 offset:22528
	ds_read_b128 v[226:229], v192 offset:23552
	global_load_lds_dwordx4 v[184:185], off
	s_add_i32 m0, s92, 0x2000
	s_add_u32 s92, s34, 0x80000
	v_lshl_add_u64 v[230:231], s[34:35], 0, v[168:169]
	s_addc_u32 s93, s35, 0
	s_add_i32 s83, s83, s38
	global_load_lds_dwordx4 v[230:231], off
	v_lshl_add_u64 v[232:233], s[92:93], 0, v[164:165]
	s_mov_b32 m0, s83
	v_lshl_add_u64 v[234:235], s[36:37], 0, v[166:167]
	global_load_lds_dwordx4 v[232:233], off
	v_lshl_add_u64 v[232:233], s[92:93], 0, v[168:169]
	s_add_i32 m0, s83, 0x2000
	s_nop 0
	global_load_lds_dwordx4 v[232:233], off
	v_lshl_add_u64 v[232:233], s[36:37], 0, v[0:1]
	s_mov_b32 m0, s39
	s_nop 0
	global_load_lds_dwordx4 v[232:233], off
	s_mov_b32 m0, s43
	s_nop 0
	global_load_lds_dwordx4 v[234:235], off
	s_waitcnt vmcnt(8)
	s_waitcnt lgkmcnt(0)
	s_setprio 1
	s_barrier
	v_mfma_f32_16x16x32_bf16 v[68:71], v[136:139], v[180:183], v[68:71]
	v_mfma_f32_16x16x32_bf16 v[64:67], v[144:147], v[180:183], v[64:67]
	v_mfma_f32_16x16x32_bf16 v[60:63], v[136:139], v[198:201], v[60:63]
	v_mfma_f32_16x16x32_bf16 v[56:59], v[144:147], v[198:201], v[56:59]
	v_mfma_f32_16x16x32_bf16 v[52:55], v[136:139], v[206:209], v[52:55]
	v_mfma_f32_16x16x32_bf16 v[48:51], v[144:147], v[206:209], v[48:51]
	v_mfma_f32_16x16x32_bf16 v[44:47], v[136:139], v[214:217], v[44:47]
	v_mfma_f32_16x16x32_bf16 v[40:43], v[144:147], v[214:217], v[40:43]
	v_mfma_f32_16x16x32_bf16 v[68:71], v[140:143], v[194:197], v[68:71]
	v_mfma_f32_16x16x32_bf16 v[64:67], v[148:151], v[194:197], v[64:67]
	v_mfma_f32_16x16x32_bf16 v[60:63], v[140:143], v[202:205], v[60:63]
	v_mfma_f32_16x16x32_bf16 v[56:59], v[148:151], v[202:205], v[56:59]
	v_mfma_f32_16x16x32_bf16 v[52:55], v[140:143], v[210:213], v[52:55]
	v_mfma_f32_16x16x32_bf16 v[48:51], v[148:151], v[210:213], v[48:51]
	v_mfma_f32_16x16x32_bf16 v[44:47], v[140:143], v[226:229], v[44:47]
	v_mfma_f32_16x16x32_bf16 v[40:43], v[148:151], v[226:229], v[40:43]
	s_setprio 0
	s_setprio 1
	v_mfma_f32_16x16x32_bf16 v[36:39], v[152:155], v[180:183], v[36:39]
	v_mfma_f32_16x16x32_bf16 v[32:35], v[160:163], v[180:183], v[32:35]
	v_mfma_f32_16x16x32_bf16 v[28:31], v[152:155], v[198:201], v[28:31]
	v_mfma_f32_16x16x32_bf16 v[24:27], v[160:163], v[198:201], v[24:27]
	v_mfma_f32_16x16x32_bf16 v[20:23], v[152:155], v[206:209], v[20:23]
	v_mfma_f32_16x16x32_bf16 v[16:19], v[160:163], v[206:209], v[16:19]
	v_mfma_f32_16x16x32_bf16 v[12:15], v[152:155], v[214:217], v[12:15]
	v_mfma_f32_16x16x32_bf16 v[4:7], v[160:163], v[214:217], v[4:7]
	v_mfma_f32_16x16x32_bf16 v[36:39], v[156:159], v[194:197], v[36:39]
	v_mfma_f32_16x16x32_bf16 v[32:35], v[176:179], v[194:197], v[32:35]
	v_mfma_f32_16x16x32_bf16 v[28:31], v[156:159], v[202:205], v[28:31]
	v_mfma_f32_16x16x32_bf16 v[24:27], v[176:179], v[202:205], v[24:27]
	v_mfma_f32_16x16x32_bf16 v[20:23], v[156:159], v[210:213], v[20:23]
	v_mfma_f32_16x16x32_bf16 v[16:19], v[176:179], v[210:213], v[16:19]
	v_mfma_f32_16x16x32_bf16 v[12:15], v[156:159], v[226:229], v[12:15]
	v_mfma_f32_16x16x32_bf16 v[4:7], v[176:179], v[226:229], v[4:7]
	s_setprio 0
	s_barrier
	s_add_i32 s83, 0, 0x18000
	s_add_i32 s92, 0, 0x1c000
	v_add_u32_e32 v148, s83, v189
	v_add_u32_e32 v176, s92, v189
	ds_read_b128 v[136:139], v148
	ds_read_b128 v[140:143], v148 offset:1024
	ds_read_b128 v[144:147], v148 offset:2048
	ds_read_b128 v[148:151], v148 offset:3072
	ds_read_b128 v[152:155], v176
	ds_read_b128 v[156:159], v176 offset:1024
	ds_read_b128 v[160:163], v176 offset:2048
	ds_read_b128 v[176:179], v176 offset:3072
	s_add_u32 s36, s36, 0x80000
	s_addc_u32 s37, s37, 0
	s_mov_b32 m0, s46
	v_lshl_add_u64 v[236:237], s[36:37], 0, v[0:1]
	ds_read_b128 v[180:183], v192 offset:32768
	ds_read_b128 v[194:197], v192 offset:33792
	ds_read_b128 v[198:201], v192 offset:34816
	ds_read_b128 v[202:205], v192 offset:35840
	ds_read_b128 v[206:209], v192 offset:36864
	ds_read_b128 v[210:213], v192 offset:37888
	ds_read_b128 v[214:217], v192 offset:38912
	ds_read_b128 v[226:229], v192 offset:39936
	global_load_lds_dwordx4 v[236:237], off
	v_lshl_add_u64 v[236:237], s[36:37], 0, v[166:167]
	s_mov_b32 m0, s47
	s_nop 0
	global_load_lds_dwordx4 v[236:237], off
	s_waitcnt vmcnt(8)
	s_waitcnt lgkmcnt(0)
	s_setprio 1
	s_barrier
	v_mfma_f32_16x16x32_bf16 v[8:11], v[136:139], v[180:183], v[8:11]
	v_mfma_f32_16x16x32_bf16 v[128:131], v[144:147], v[180:183], v[128:131]
	v_mfma_f32_16x16x32_bf16 v[124:127], v[136:139], v[198:201], v[124:127]
	v_mfma_f32_16x16x32_bf16 v[120:123], v[144:147], v[198:201], v[120:123]
	v_mfma_f32_16x16x32_bf16 v[116:119], v[136:139], v[206:209], v[116:119]
	v_mfma_f32_16x16x32_bf16 v[112:115], v[144:147], v[206:209], v[112:115]
	v_mfma_f32_16x16x32_bf16 v[108:111], v[136:139], v[214:217], v[108:111]
	v_mfma_f32_16x16x32_bf16 v[104:107], v[144:147], v[214:217], v[104:107]
	v_mfma_f32_16x16x32_bf16 v[8:11], v[140:143], v[194:197], v[8:11]
	v_mfma_f32_16x16x32_bf16 v[128:131], v[148:151], v[194:197], v[128:131]
	v_mfma_f32_16x16x32_bf16 v[124:127], v[140:143], v[202:205], v[124:127]
	v_mfma_f32_16x16x32_bf16 v[120:123], v[148:151], v[202:205], v[120:123]
	v_mfma_f32_16x16x32_bf16 v[116:119], v[140:143], v[210:213], v[116:119]
	v_mfma_f32_16x16x32_bf16 v[112:115], v[148:151], v[210:213], v[112:115]
	v_mfma_f32_16x16x32_bf16 v[108:111], v[140:143], v[226:229], v[108:111]
	v_mfma_f32_16x16x32_bf16 v[104:107], v[148:151], v[226:229], v[104:107]
	s_setprio 0
	s_setprio 1
	v_mfma_f32_16x16x32_bf16 v[100:103], v[152:155], v[180:183], v[100:103]
	v_mfma_f32_16x16x32_bf16 v[96:99], v[160:163], v[180:183], v[96:99]
	v_mfma_f32_16x16x32_bf16 v[92:95], v[152:155], v[198:201], v[92:95]
	v_mfma_f32_16x16x32_bf16 v[88:91], v[160:163], v[198:201], v[88:91]
	v_mfma_f32_16x16x32_bf16 v[84:87], v[152:155], v[206:209], v[84:87]
	v_mfma_f32_16x16x32_bf16 v[80:83], v[160:163], v[206:209], v[80:83]
	v_mfma_f32_16x16x32_bf16 v[76:79], v[152:155], v[214:217], v[76:79]
	v_mfma_f32_16x16x32_bf16 v[72:75], v[160:163], v[214:217], v[72:75]
	v_mfma_f32_16x16x32_bf16 v[100:103], v[156:159], v[194:197], v[100:103]
	v_mfma_f32_16x16x32_bf16 v[96:99], v[176:179], v[194:197], v[96:99]
	v_mfma_f32_16x16x32_bf16 v[92:95], v[156:159], v[202:205], v[92:95]
	v_mfma_f32_16x16x32_bf16 v[88:91], v[176:179], v[202:205], v[88:91]
	v_mfma_f32_16x16x32_bf16 v[84:87], v[156:159], v[210:213], v[84:87]
	v_mfma_f32_16x16x32_bf16 v[80:83], v[176:179], v[210:213], v[80:83]
	v_mfma_f32_16x16x32_bf16 v[76:79], v[156:159], v[226:229], v[76:79]
	v_mfma_f32_16x16x32_bf16 v[72:75], v[176:179], v[226:229], v[72:75]
	s_setprio 0
	s_barrier
	s_add_i32 s36, s83, s38
	v_lshl_add_u64 v[184:185], v[184:185], 0, s[70:71]
	s_mov_b32 m0, s36
	ds_read_b128 v[180:183], v192 offset:49152
	ds_read_b128 v[194:197], v192 offset:50176
	ds_read_b128 v[198:201], v192 offset:51200
	ds_read_b128 v[202:205], v192 offset:52224
	ds_read_b128 v[206:209], v192 offset:53248
	ds_read_b128 v[210:213], v192 offset:54272
	ds_read_b128 v[214:217], v192 offset:55296
	ds_read_b128 v[226:229], v192 offset:56320
	global_load_lds_dwordx4 v[184:185], off
	s_add_i32 m0, s36, 0x2000
	s_add_u32 s34, s34, 0x80080
	v_lshl_add_u64 v[184:185], v[230:231], 0, s[70:71]
	s_addc_u32 s35, s35, 0
	s_add_i32 s36, s92, s38
	global_load_lds_dwordx4 v[184:185], off
	v_lshl_add_u64 v[184:185], s[34:35], 0, v[164:165]
	s_mov_b32 m0, s36
	s_nop 0
	global_load_lds_dwordx4 v[184:185], off
	v_lshl_add_u64 v[184:185], s[34:35], 0, v[168:169]
	s_add_i32 m0, s36, 0x2000
	s_nop 0
	global_load_lds_dwordx4 v[184:185], off
	v_lshl_add_u64 v[184:185], v[232:233], 0, s[70:71]
	s_mov_b32 m0, s51
	s_nop 0
	global_load_lds_dwordx4 v[184:185], off
	v_lshl_add_u64 v[184:185], v[234:235], 0, s[70:71]
	s_mov_b32 m0, s52
	s_nop 0
	global_load_lds_dwordx4 v[184:185], off
	s_waitcnt vmcnt(8)
	s_waitcnt lgkmcnt(0)
	s_setprio 1
	s_barrier
	v_mfma_f32_16x16x32_bf16 v[68:71], v[136:139], v[180:183], v[68:71]
	v_mfma_f32_16x16x32_bf16 v[64:67], v[144:147], v[180:183], v[64:67]
	v_mfma_f32_16x16x32_bf16 v[60:63], v[136:139], v[198:201], v[60:63]
	v_mfma_f32_16x16x32_bf16 v[56:59], v[144:147], v[198:201], v[56:59]
	v_mfma_f32_16x16x32_bf16 v[52:55], v[136:139], v[206:209], v[52:55]
	v_mfma_f32_16x16x32_bf16 v[48:51], v[144:147], v[206:209], v[48:51]
	v_mfma_f32_16x16x32_bf16 v[44:47], v[136:139], v[214:217], v[44:47]
	v_mfma_f32_16x16x32_bf16 v[40:43], v[144:147], v[214:217], v[40:43]
	v_mfma_f32_16x16x32_bf16 v[68:71], v[140:143], v[194:197], v[68:71]
	v_mfma_f32_16x16x32_bf16 v[64:67], v[148:151], v[194:197], v[64:67]
	v_mfma_f32_16x16x32_bf16 v[60:63], v[140:143], v[202:205], v[60:63]
	v_mfma_f32_16x16x32_bf16 v[56:59], v[148:151], v[202:205], v[56:59]
	v_mfma_f32_16x16x32_bf16 v[52:55], v[140:143], v[210:213], v[52:55]
	v_mfma_f32_16x16x32_bf16 v[48:51], v[148:151], v[210:213], v[48:51]
	v_mfma_f32_16x16x32_bf16 v[44:47], v[140:143], v[226:229], v[44:47]
	v_mfma_f32_16x16x32_bf16 v[40:43], v[148:151], v[226:229], v[40:43]
	s_setprio 0
	s_setprio 1
	v_mfma_f32_16x16x32_bf16 v[36:39], v[152:155], v[180:183], v[36:39]
	v_mfma_f32_16x16x32_bf16 v[32:35], v[160:163], v[180:183], v[32:35]
	v_mfma_f32_16x16x32_bf16 v[28:31], v[152:155], v[198:201], v[28:31]
	v_mfma_f32_16x16x32_bf16 v[24:27], v[160:163], v[198:201], v[24:27]
	v_mfma_f32_16x16x32_bf16 v[20:23], v[152:155], v[206:209], v[20:23]
	v_mfma_f32_16x16x32_bf16 v[16:19], v[160:163], v[206:209], v[16:19]
	v_mfma_f32_16x16x32_bf16 v[12:15], v[152:155], v[214:217], v[12:15]
	v_mfma_f32_16x16x32_bf16 v[4:7], v[160:163], v[214:217], v[4:7]
	v_mfma_f32_16x16x32_bf16 v[36:39], v[156:159], v[194:197], v[36:39]
	v_mfma_f32_16x16x32_bf16 v[32:35], v[176:179], v[194:197], v[32:35]
	v_mfma_f32_16x16x32_bf16 v[28:31], v[156:159], v[202:205], v[28:31]
	v_mfma_f32_16x16x32_bf16 v[24:27], v[176:179], v[202:205], v[24:27]
	v_mfma_f32_16x16x32_bf16 v[20:23], v[156:159], v[210:213], v[20:23]
	v_mfma_f32_16x16x32_bf16 v[16:19], v[176:179], v[210:213], v[16:19]
	v_mfma_f32_16x16x32_bf16 v[12:15], v[156:159], v[226:229], v[12:15]
	v_mfma_f32_16x16x32_bf16 v[4:7], v[176:179], v[226:229], v[4:7]
	s_setprio 0
	s_barrier
	s_add_i32 s85, s85, 2
	s_add_u32 s12, s12, 0x100
	s_addc_u32 s13, s13, 0
	s_cmp_gt_u32 s85, 29
	s_cbranch_scc0 .LBB0_1067
	s_and_b64 vcc, exec, s[20:21]
	s_cbranch_vccz .LBB0_1070
	s_barrier

.LBB0_1205:
	v_add_u32_e32 v144, 0x10000, v182
	v_add_u32_e32 v170, 0x14000, v182
	ds_read_b128 v[132:135], v144
	ds_read_b128 v[136:139], v144 offset:1024
	ds_read_b128 v[140:143], v144 offset:2048
	ds_read_b128 v[144:147], v144 offset:3072
	ds_read_b128 v[148:151], v170
	ds_read_b128 v[152:155], v170 offset:1024
	ds_read_b128 v[156:159], v170 offset:2048
	ds_read_b128 v[170:173], v170 offset:3072
	v_lshl_add_u64 v[212:213], s[22:23], 0, v[166:167]
	s_add_i32 m0, s31, 0xc000
	ds_read_b128 v[174:177], v186
	ds_read_b128 v[178:181], v186 offset:1024
	ds_read_b128 v[188:191], v186 offset:2048
	ds_read_b128 v[192:195], v186 offset:3072
	ds_read_b128 v[196:199], v186 offset:4096
	ds_read_b128 v[200:203], v186 offset:5120
	ds_read_b128 v[204:207], v186 offset:6144
	ds_read_b128 v[208:211], v186 offset:7168
	s_add_u32 s24, s22, 0x100
	s_addc_u32 s25, s23, 0
	s_add_i32 s67, 0, 0x10000
	s_cmpk_eq_i32 s66, 0x54
	s_cselect_b32 s29, s9, s25
	s_cselect_b32 s28, s8, s24
	s_cselect_b32 s27, s21, s54
	s_cselect_b32 s26, s20, s52
	s_add_i32 s69, 0, 0x14000
	global_load_lds_dwordx4 v[212:213], off
	v_lshl_add_u64 v[212:213], s[22:23], 0, v[168:169]
	s_add_i32 m0, s31, 0xe000
	s_nop 0
	global_load_lds_dwordx4 v[212:213], off
	s_waitcnt vmcnt(8)
	s_waitcnt lgkmcnt(0)
	s_setprio 1
	s_barrier
	v_mfma_f32_16x16x32_bf16 v[128:131], v[132:135], v[174:177], v[128:131]
	v_mfma_f32_16x16x32_bf16 v[124:127], v[140:143], v[174:177], v[124:127]
	v_mfma_f32_16x16x32_bf16 v[112:115], v[132:135], v[188:191], v[112:115]
	v_mfma_f32_16x16x32_bf16 v[108:111], v[140:143], v[188:191], v[108:111]
	v_mfma_f32_16x16x32_bf16 v[96:99], v[132:135], v[196:199], v[96:99]
	v_mfma_f32_16x16x32_bf16 v[92:95], v[140:143], v[196:199], v[92:95]
	v_mfma_f32_16x16x32_bf16 v[80:83], v[132:135], v[204:207], v[80:83]
	v_mfma_f32_16x16x32_bf16 v[76:79], v[140:143], v[204:207], v[76:79]
	v_mfma_f32_16x16x32_bf16 v[128:131], v[136:139], v[178:181], v[128:131]
	v_mfma_f32_16x16x32_bf16 v[124:127], v[144:147], v[178:181], v[124:127]
	v_mfma_f32_16x16x32_bf16 v[112:115], v[136:139], v[192:195], v[112:115]
	v_mfma_f32_16x16x32_bf16 v[108:111], v[144:147], v[192:195], v[108:111]
	v_mfma_f32_16x16x32_bf16 v[96:99], v[136:139], v[200:203], v[96:99]
	v_mfma_f32_16x16x32_bf16 v[92:95], v[144:147], v[200:203], v[92:95]
	v_mfma_f32_16x16x32_bf16 v[80:83], v[136:139], v[208:211], v[80:83]
	v_mfma_f32_16x16x32_bf16 v[76:79], v[144:147], v[208:211], v[76:79]
	s_setprio 0
	s_setprio 1
	v_mfma_f32_16x16x32_bf16 v[120:123], v[148:151], v[174:177], v[120:123]
	v_mfma_f32_16x16x32_bf16 v[116:119], v[156:159], v[174:177], v[116:119]
	v_mfma_f32_16x16x32_bf16 v[104:107], v[148:151], v[188:191], v[104:107]
	v_mfma_f32_16x16x32_bf16 v[100:103], v[156:159], v[188:191], v[100:103]
	v_mfma_f32_16x16x32_bf16 v[88:91], v[148:151], v[196:199], v[88:91]
	v_mfma_f32_16x16x32_bf16 v[84:87], v[156:159], v[196:199], v[84:87]
	v_mfma_f32_16x16x32_bf16 v[72:75], v[148:151], v[204:207], v[72:75]
	v_mfma_f32_16x16x32_bf16 v[68:71], v[156:159], v[204:207], v[68:71]
	v_mfma_f32_16x16x32_bf16 v[120:123], v[152:155], v[178:181], v[120:123]
	v_mfma_f32_16x16x32_bf16 v[116:119], v[170:173], v[178:181], v[116:119]
	v_mfma_f32_16x16x32_bf16 v[104:107], v[152:155], v[192:195], v[104:107]
	v_mfma_f32_16x16x32_bf16 v[100:103], v[170:173], v[192:195], v[100:103]
	v_mfma_f32_16x16x32_bf16 v[88:91], v[152:155], v[200:203], v[88:91]
	v_mfma_f32_16x16x32_bf16 v[84:87], v[170:173], v[200:203], v[84:87]
	v_mfma_f32_16x16x32_bf16 v[72:75], v[152:155], v[208:211], v[72:75]
	v_mfma_f32_16x16x32_bf16 v[68:71], v[170:173], v[208:211], v[68:71]
	s_setprio 0
	s_barrier
	s_add_i32 s22, s67, s30
	v_lshl_add_u64 v[212:213], s[26:27], 0, v[162:163]
	s_mov_b32 m0, s22
	ds_read_b128 v[174:177], v186 offset:16384
	ds_read_b128 v[178:181], v186 offset:17408
	ds_read_b128 v[188:191], v186 offset:18432
	ds_read_b128 v[192:195], v186 offset:19456
	ds_read_b128 v[196:199], v186 offset:20480
	ds_read_b128 v[200:203], v186 offset:21504
	ds_read_b128 v[204:207], v186 offset:22528
	ds_read_b128 v[208:211], v186 offset:23552
	global_load_lds_dwordx4 v[212:213], off
	s_add_i32 m0, s22, 0x2000
	s_add_u32 s22, s26, 0x160000
	v_lshl_add_u64 v[214:215], s[26:27], 0, v[0:1]
	s_addc_u32 s23, s27, 0
	s_add_i32 s67, s69, s30
	global_load_lds_dwordx4 v[214:215], off
	v_lshl_add_u64 v[216:217], s[22:23], 0, v[162:163]
	s_mov_b32 m0, s67
	v_lshl_add_u64 v[226:227], s[28:29], 0, v[160:161]
	global_load_lds_dwordx4 v[216:217], off
	v_lshl_add_u64 v[216:217], s[22:23], 0, v[0:1]
	s_add_i32 m0, s67, 0x2000
	s_nop 0
	global_load_lds_dwordx4 v[216:217], off
	v_lshl_add_u64 v[216:217], s[28:29], 0, v[164:165]
	s_mov_b32 m0, s31
	s_nop 0
	global_load_lds_dwordx4 v[216:217], off
	s_mov_b32 m0, s34
	s_nop 0
	global_load_lds_dwordx4 v[226:227], off
	s_waitcnt vmcnt(8)
	s_waitcnt lgkmcnt(0)
	s_setprio 1
	s_barrier
	v_mfma_f32_16x16x32_bf16 v[64:67], v[132:135], v[174:177], v[64:67]
	v_mfma_f32_16x16x32_bf16 v[60:63], v[140:143], v[174:177], v[60:63]
	v_mfma_f32_16x16x32_bf16 v[48:51], v[132:135], v[188:191], v[48:51]
	v_mfma_f32_16x16x32_bf16 v[44:47], v[140:143], v[188:191], v[44:47]
	v_mfma_f32_16x16x32_bf16 v[32:35], v[132:135], v[196:199], v[32:35]
	v_mfma_f32_16x16x32_bf16 v[28:31], v[140:143], v[196:199], v[28:31]
	v_mfma_f32_16x16x32_bf16 v[16:19], v[132:135], v[204:207], v[16:19]
	v_mfma_f32_16x16x32_bf16 v[12:15], v[140:143], v[204:207], v[12:15]
	v_mfma_f32_16x16x32_bf16 v[64:67], v[136:139], v[178:181], v[64:67]
	v_mfma_f32_16x16x32_bf16 v[60:63], v[144:147], v[178:181], v[60:63]
	v_mfma_f32_16x16x32_bf16 v[48:51], v[136:139], v[192:195], v[48:51]
	v_mfma_f32_16x16x32_bf16 v[44:47], v[144:147], v[192:195], v[44:47]
	v_mfma_f32_16x16x32_bf16 v[32:35], v[136:139], v[200:203], v[32:35]
	v_mfma_f32_16x16x32_bf16 v[28:31], v[144:147], v[200:203], v[28:31]
	v_mfma_f32_16x16x32_bf16 v[16:19], v[136:139], v[208:211], v[16:19]
	v_mfma_f32_16x16x32_bf16 v[12:15], v[144:147], v[208:211], v[12:15]
	s_setprio 0
	s_setprio 1
	v_mfma_f32_16x16x32_bf16 v[56:59], v[148:151], v[174:177], v[56:59]
	v_mfma_f32_16x16x32_bf16 v[52:55], v[156:159], v[174:177], v[52:55]
	v_mfma_f32_16x16x32_bf16 v[40:43], v[148:151], v[188:191], v[40:43]
	v_mfma_f32_16x16x32_bf16 v[36:39], v[156:159], v[188:191], v[36:39]
	v_mfma_f32_16x16x32_bf16 v[24:27], v[148:151], v[196:199], v[24:27]
	v_mfma_f32_16x16x32_bf16 v[20:23], v[156:159], v[196:199], v[20:23]
	v_mfma_f32_16x16x32_bf16 v[8:11], v[148:151], v[204:207], v[8:11]
	v_mfma_f32_16x16x32_bf16 v[4:7], v[156:159], v[204:207], v[4:7]
	v_mfma_f32_16x16x32_bf16 v[56:59], v[152:155], v[178:181], v[56:59]
	v_mfma_f32_16x16x32_bf16 v[52:55], v[170:173], v[178:181], v[52:55]
	v_mfma_f32_16x16x32_bf16 v[40:43], v[152:155], v[192:195], v[40:43]
	v_mfma_f32_16x16x32_bf16 v[36:39], v[170:173], v[192:195], v[36:39]
	v_mfma_f32_16x16x32_bf16 v[24:27], v[152:155], v[200:203], v[24:27]
	v_mfma_f32_16x16x32_bf16 v[20:23], v[170:173], v[200:203], v[20:23]
	v_mfma_f32_16x16x32_bf16 v[8:11], v[152:155], v[208:211], v[8:11]
	v_mfma_f32_16x16x32_bf16 v[4:7], v[170:173], v[208:211], v[4:7]
	s_setprio 0
	s_barrier
	s_add_i32 s67, 0, 0x18000
	s_add_i32 s69, 0, 0x1c000
	v_add_u32_e32 v144, s67, v182
	v_add_u32_e32 v170, s69, v182
	ds_read_b128 v[132:135], v144
	ds_read_b128 v[136:139], v144 offset:1024
	ds_read_b128 v[140:143], v144 offset:2048
	ds_read_b128 v[144:147], v144 offset:3072
	ds_read_b128 v[148:151], v170
	ds_read_b128 v[152:155], v170 offset:1024
	ds_read_b128 v[156:159], v170 offset:2048
	ds_read_b128 v[170:173], v170 offset:3072
	s_add_u32 s22, s28, 0x160000
	s_addc_u32 s23, s29, 0
	s_mov_b32 m0, s35
	v_lshl_add_u64 v[228:229], s[22:23], 0, v[164:165]
	ds_read_b128 v[174:177], v186 offset:32768
	ds_read_b128 v[178:181], v186 offset:33792
	ds_read_b128 v[188:191], v186 offset:34816
	ds_read_b128 v[192:195], v186 offset:35840
	ds_read_b128 v[196:199], v186 offset:36864
	ds_read_b128 v[200:203], v186 offset:37888
	ds_read_b128 v[204:207], v186 offset:38912
	ds_read_b128 v[208:211], v186 offset:39936
	global_load_lds_dwordx4 v[228:229], off
	v_lshl_add_u64 v[228:229], s[22:23], 0, v[160:161]
	s_mov_b32 m0, s36
	s_nop 0
	global_load_lds_dwordx4 v[228:229], off
	s_waitcnt vmcnt(8)
	s_waitcnt lgkmcnt(0)
	s_setprio 1
	s_barrier
	v_mfma_f32_16x16x32_bf16 v[128:131], v[132:135], v[174:177], v[128:131]
	v_mfma_f32_16x16x32_bf16 v[124:127], v[140:143], v[174:177], v[124:127]
	v_mfma_f32_16x16x32_bf16 v[112:115], v[132:135], v[188:191], v[112:115]
	v_mfma_f32_16x16x32_bf16 v[108:111], v[140:143], v[188:191], v[108:111]
	v_mfma_f32_16x16x32_bf16 v[96:99], v[132:135], v[196:199], v[96:99]
	v_mfma_f32_16x16x32_bf16 v[92:95], v[140:143], v[196:199], v[92:95]
	v_mfma_f32_16x16x32_bf16 v[80:83], v[132:135], v[204:207], v[80:83]
	v_mfma_f32_16x16x32_bf16 v[76:79], v[140:143], v[204:207], v[76:79]
	v_mfma_f32_16x16x32_bf16 v[128:131], v[136:139], v[178:181], v[128:131]
	v_mfma_f32_16x16x32_bf16 v[124:127], v[144:147], v[178:181], v[124:127]
	v_mfma_f32_16x16x32_bf16 v[112:115], v[136:139], v[192:195], v[112:115]
	v_mfma_f32_16x16x32_bf16 v[108:111], v[144:147], v[192:195], v[108:111]
	v_mfma_f32_16x16x32_bf16 v[96:99], v[136:139], v[200:203], v[96:99]
	v_mfma_f32_16x16x32_bf16 v[92:95], v[144:147], v[200:203], v[92:95]
	v_mfma_f32_16x16x32_bf16 v[80:83], v[136:139], v[208:211], v[80:83]
	v_mfma_f32_16x16x32_bf16 v[76:79], v[144:147], v[208:211], v[76:79]
	s_setprio 0
	s_setprio 1
	v_mfma_f32_16x16x32_bf16 v[120:123], v[148:151], v[174:177], v[120:123]
	v_mfma_f32_16x16x32_bf16 v[116:119], v[156:159], v[174:177], v[116:119]
	v_mfma_f32_16x16x32_bf16 v[104:107], v[148:151], v[188:191], v[104:107]
	v_mfma_f32_16x16x32_bf16 v[100:103], v[156:159], v[188:191], v[100:103]
	v_mfma_f32_16x16x32_bf16 v[88:91], v[148:151], v[196:199], v[88:91]
	v_mfma_f32_16x16x32_bf16 v[84:87], v[156:159], v[196:199], v[84:87]
	v_mfma_f32_16x16x32_bf16 v[72:75], v[148:151], v[204:207], v[72:75]
	v_mfma_f32_16x16x32_bf16 v[68:71], v[156:159], v[204:207], v[68:71]
	v_mfma_f32_16x16x32_bf16 v[120:123], v[152:155], v[178:181], v[120:123]
	v_mfma_f32_16x16x32_bf16 v[116:119], v[170:173], v[178:181], v[116:119]
	v_mfma_f32_16x16x32_bf16 v[104:107], v[152:155], v[192:195], v[104:107]
	v_mfma_f32_16x16x32_bf16 v[100:103], v[170:173], v[192:195], v[100:103]
	v_mfma_f32_16x16x32_bf16 v[88:91], v[152:155], v[200:203], v[88:91]
	v_mfma_f32_16x16x32_bf16 v[84:87], v[170:173], v[200:203], v[84:87]
	v_mfma_f32_16x16x32_bf16 v[72:75], v[152:155], v[208:211], v[72:75]
	v_mfma_f32_16x16x32_bf16 v[68:71], v[170:173], v[208:211], v[68:71]
	s_setprio 0
	s_barrier
	s_add_i32 s22, s67, s30
	v_lshl_add_u64 v[212:213], v[212:213], 0, s[70:71]
	s_mov_b32 m0, s22
	ds_read_b128 v[174:177], v186 offset:49152
	ds_read_b128 v[178:181], v186 offset:50176
	ds_read_b128 v[188:191], v186 offset:51200
	ds_read_b128 v[192:195], v186 offset:52224
	ds_read_b128 v[196:199], v186 offset:53248
	ds_read_b128 v[200:203], v186 offset:54272
	ds_read_b128 v[204:207], v186 offset:55296
	ds_read_b128 v[208:211], v186 offset:56320
	global_load_lds_dwordx4 v[212:213], off
	s_add_i32 m0, s22, 0x2000
	s_add_u32 s22, s26, 0x160080
	v_lshl_add_u64 v[212:213], v[214:215], 0, s[70:71]
	s_addc_u32 s23, s27, 0
	s_add_i32 s26, s69, s30
	global_load_lds_dwordx4 v[212:213], off
	v_lshl_add_u64 v[212:213], s[22:23], 0, v[162:163]
	s_mov_b32 m0, s26
	s_nop 0
	global_load_lds_dwordx4 v[212:213], off
	v_lshl_add_u64 v[212:213], s[22:23], 0, v[0:1]
	s_add_i32 m0, s26, 0x2000
	s_nop 0
	global_load_lds_dwordx4 v[212:213], off
	v_lshl_add_u64 v[212:213], v[216:217], 0, s[70:71]
	s_mov_b32 m0, s38
	s_nop 0
	global_load_lds_dwordx4 v[212:213], off
	v_lshl_add_u64 v[212:213], v[226:227], 0, s[70:71]
	s_mov_b32 m0, s39
	s_nop 0
	global_load_lds_dwordx4 v[212:213], off
	s_waitcnt vmcnt(8)
	s_waitcnt lgkmcnt(0)
	s_setprio 1
	s_barrier
	v_mfma_f32_16x16x32_bf16 v[64:67], v[132:135], v[174:177], v[64:67]
	v_mfma_f32_16x16x32_bf16 v[60:63], v[140:143], v[174:177], v[60:63]
	v_mfma_f32_16x16x32_bf16 v[48:51], v[132:135], v[188:191], v[48:51]
	v_mfma_f32_16x16x32_bf16 v[44:47], v[140:143], v[188:191], v[44:47]
	v_mfma_f32_16x16x32_bf16 v[32:35], v[132:135], v[196:199], v[32:35]
	v_mfma_f32_16x16x32_bf16 v[28:31], v[140:143], v[196:199], v[28:31]
	v_mfma_f32_16x16x32_bf16 v[16:19], v[132:135], v[204:207], v[16:19]
	v_mfma_f32_16x16x32_bf16 v[12:15], v[140:143], v[204:207], v[12:15]
	v_mfma_f32_16x16x32_bf16 v[64:67], v[136:139], v[178:181], v[64:67]
	v_mfma_f32_16x16x32_bf16 v[60:63], v[144:147], v[178:181], v[60:63]
	v_mfma_f32_16x16x32_bf16 v[48:51], v[136:139], v[192:195], v[48:51]
	v_mfma_f32_16x16x32_bf16 v[44:47], v[144:147], v[192:195], v[44:47]
	v_mfma_f32_16x16x32_bf16 v[32:35], v[136:139], v[200:203], v[32:35]
	v_mfma_f32_16x16x32_bf16 v[28:31], v[144:147], v[200:203], v[28:31]
	v_mfma_f32_16x16x32_bf16 v[16:19], v[136:139], v[208:211], v[16:19]
	v_mfma_f32_16x16x32_bf16 v[12:15], v[144:147], v[208:211], v[12:15]
	s_setprio 0
	s_setprio 1
	v_mfma_f32_16x16x32_bf16 v[56:59], v[148:151], v[174:177], v[56:59]
	v_mfma_f32_16x16x32_bf16 v[52:55], v[156:159], v[174:177], v[52:55]
	v_mfma_f32_16x16x32_bf16 v[40:43], v[148:151], v[188:191], v[40:43]
	v_mfma_f32_16x16x32_bf16 v[36:39], v[156:159], v[188:191], v[36:39]
	v_mfma_f32_16x16x32_bf16 v[24:27], v[148:151], v[196:199], v[24:27]
	v_mfma_f32_16x16x32_bf16 v[20:23], v[156:159], v[196:199], v[20:23]
	v_mfma_f32_16x16x32_bf16 v[8:11], v[148:151], v[204:207], v[8:11]
	v_mfma_f32_16x16x32_bf16 v[4:7], v[156:159], v[204:207], v[4:7]
	v_mfma_f32_16x16x32_bf16 v[56:59], v[152:155], v[178:181], v[56:59]
	v_mfma_f32_16x16x32_bf16 v[52:55], v[170:173], v[178:181], v[52:55]
	v_mfma_f32_16x16x32_bf16 v[40:43], v[152:155], v[192:195], v[40:43]
	v_mfma_f32_16x16x32_bf16 v[36:39], v[170:173], v[192:195], v[36:39]
	v_mfma_f32_16x16x32_bf16 v[24:27], v[152:155], v[200:203], v[24:27]
	v_mfma_f32_16x16x32_bf16 v[20:23], v[170:173], v[200:203], v[20:23]
	v_mfma_f32_16x16x32_bf16 v[8:11], v[152:155], v[208:211], v[8:11]
	v_mfma_f32_16x16x32_bf16 v[4:7], v[170:173], v[208:211], v[4:7]
	s_setprio 0
	s_barrier
	s_add_i32 s66, s66, 2
	s_add_u32 s52, s52, 0x100
	s_addc_u32 s54, s54, 0
	s_cmpk_gt_u32 s66, 0x55
	s_mov_b64 s[22:23], s[24:25]
	s_cbranch_scc0 .LBB0_1205
	s_and_b64 vcc, exec, s[18:19]
	s_cbranch_vccz .LBB0_1208
	s_barrier
